# up-projection epilogue: 54 v_mov copies that only built register pairs for the former v_pk_mul are forwarded into the v_fma that replaced it and removed
# speedup vs baseline: 1.0018x; 1.0000x over previous
;     __device__ __forceinline__ void operator()(const f32x4 (&acc)[2][2][4][2], const Unit& u, int wr, int wc, int fr, int fq) const {
;     ...
;         const int lane = otid() & 63;
;         const int src1 = (lane & 48) | ((fr + 15) & 15), src2 = (lane & 48) | ((fr + 14) & 15);
;         float rs[2][4];
; #pragma unroll
;         for (int ai = 0; ai < 2; ++ai)
; #pragma unroll
;             for (int m = 0; m < 4; ++m) rs[ai][m] = __builtin_amdgcn_rsqf((float)ss[u.pm * BM + ai * HALF + wr * 64 + m * 16 + fr] * (1.f / (2048.f * 262144.f)) + 1e-6f);
; #pragma unroll
;         for (int n = 0; n < 2; ++n) {
;             const int cbase = 128 * u.pn + 32 * wc + 16 * n + 4 * fq;
;             const f32x4 w0 = *(const f32x4*)(cw + cbase), w1 = *(const f32x4*)(cw + FF + cbase), w2 = *(const f32x4*)(cw + 2 * FF + cbase), b4 = *(const f32x4*)(cb + cbase);
; #pragma unroll
;             for (int ai = 0; ai < 2; ++ai) {
;                 const int slab = u.pm * 4 + 2 * ai + wr;
;                 f32x4 r1p = (f32x4){0.f, 0.f, 0.f, 0.f}, r2p = (f32x4){0.f, 0.f, 0.f, 0.f};
; #pragma unroll
;                 for (int m = 0; m < 4; ++m) {
;                     const f32x4 g = acc[ai][1][m][n] * rs[ai][m], v = acc[ai][0][m][n] * rs[ai][m];
;                     f32x4 r1, r2, a;
; #pragma unroll
;                     for (int e = 0; e < 4; ++e) { r1[e] = __shfl(g[e], src1); r2[e] = __shfl(g[e], src2); }
; #pragma unroll
;                     for (int e = 0; e < 4; ++e) {
;                         const float p1 = fr >= 1 ? r1[e] : r1p[e], p2 = fr >= 2 ? r2[e] : r2p[e];
;                         const float gg = b4[e] + w0[e] * p2 + w1[e] * p1 + w2[e] * g[e];
;                         a[e] = gg * __builtin_amdgcn_rcpf(1.f + __expf(-gg)) * v[e];
;                     }
;                     r1p = r1; r2p = r2;
;                     const size_t row = (size_t)(u.pm * BM + ai * HALF + wr * 64 + m * 16 + fr);
;                     if (m == 0 && fr < 2) {
;                         *(f32x4*)(GF + (size_t)(slab * 2 + fr) * FF + cbase) = g; *(f32x4*)(VF + (size_t)(slab * 2 + fr) * FF + cbase) = v;
;                     } else {
;                         typedef unsigned u32x2v __attribute__((ext_vector_type(2)));
;                         u32x2v w; w.x = cvt_pk_bf16(a[0], a[1]); w.y = cvt_pk_bf16(a[2], a[3]);
;                         *(u32x2v*)(ACT + row * FF + cbase) = w;
.LBB0_41:
	v_lshl_add_u32 v160, s66, 8, v193
	v_ashrrev_i32_e32 v161, 31, v160
	v_mov_b32_e32 v148, v227
	v_bfe_u32 v205, v227, 4, 1
	v_mul_u32_u24_e32 v205, 24, v205
	s_and_b32 s98, s65, 1
	s_lshl_b32 s98, s98, 12
	s_add_i32 s98, s98, 0x20000
	s_add_i32 s99, s98, 0x800
	v_lshl_add_u32 v114, v193, 3, s98
	ds_read_b64 v[146:147], v114
	v_lshl_or_b32 v156, s64, 7, v198
	v_ashrrev_i32_e32 v157, 31, v156
	ds_read_b64 v[190:191], v114 offset:128
	ds_read_b64 v[188:189], v114 offset:256
	ds_read_b64 v[186:187], v114 offset:384
	ds_read_b64 v[176:177], v114 offset:1024
	ds_read_b64 v[174:175], v114 offset:1152
	ds_read_b64 v[172:173], v114 offset:1280
	ds_read_b64 v[170:171], v114 offset:1408
	v_lshlrev_b64 v[158:159], 2, v[156:157]
	v_lshl_add_u32 v166, v198, 2, s99
	v_lshl_add_u64 v[118:119], s[60:61], 0, v[158:159]
	v_lshl_add_u64 v[120:121], s[62:63], 0, v[158:159]
	v_lshl_add_u64 v[164:165], s[54:55], 0, v[158:159]
	ds_read_b128 v[114:117], v166
	ds_read_b128 v[138:141], v166 offset:512
	ds_read_b128 v[130:133], v166 offset:1024
	s_nop 0
	ds_read_b128 v[118:121], v166 offset:1536
	s_waitcnt lgkmcnt(0)
	v_ffbh_u32_e32 v149, v147
	v_min_u32_e32 v149, 32, v149
	v_lshlrev_b64 v[146:147], v149, v[146:147]
	v_min_u32_e32 v146, 1, v146
	v_or_b32_e32 v146, v147, v146
	v_cvt_f32_u32_e32 v146, v146
	v_sub_u32_e32 v149, 32, v149
	v_and_b32_e32 v147, 48, v148
	v_or3_b32 v148, v147, v195, v236
	v_ldexp_f32 v146, v146, v149
	v_fmamk_f32 v146, v146, 0x31000000, v232
	v_rsq_f32_e32 v162, v146
	v_or3_b32 v146, v147, v196, v236
	v_lshlrev_b32_e32 v200, 2, v146
	v_lshlrev_b32_e32 v161, 2, v148
	v_pk_mul_f32 v[146:147], v[134:135], v[162:163] op_sel_hi:[1,0]
	v_pk_mul_f32 v[148:149], v[136:137], v[162:163] op_sel_hi:[1,0]
	s_nop 1
	v_mov_b32_dpp v163, v146 row_ror:2 row_mask:0xf bank_mask:0xf
	v_mov_b32_dpp v179, v146 row_ror:1 row_mask:0xf bank_mask:0xf
	v_mov_b32_dpp v181, v147 row_ror:1 row_mask:0xf bank_mask:0xf
	v_mov_b32_dpp v201, v147 row_ror:2 row_mask:0xf bank_mask:0xf
	v_mov_b32_dpp v183, v148 row_ror:1 row_mask:0xf bank_mask:0xf
	v_mov_b32_dpp v202, v148 row_ror:2 row_mask:0xf bank_mask:0xf
	v_mov_b32_dpp v185, v149 row_ror:1 row_mask:0xf bank_mask:0xf
	v_mov_b32_dpp v203, v149 row_ror:2 row_mask:0xf bank_mask:0xf
	s_waitcnt lgkmcnt(7)
	v_pk_mul_f32 v[136:137], v[144:145], v[162:163] op_sel_hi:[1,0]
	v_pk_mul_f32 v[134:135], v[142:143], v[162:163] op_sel_hi:[1,0]
	s_and_saveexec_b64 s[10:11], s[42:43]
	s_xor_b64 s[10:11], exec, s[10:11]
	s_movk_i32 s17, 0x2b00
	s_movk_i32 s84, 0x300
	s_mov_b32 s86, 0x24000
	s_mov_b32 s88, 0x48800000
	s_cbranch_execz .LBB0_43
	v_mov_b32_e32 v184, v133
	s_waitcnt lgkmcnt(1)
	s_waitcnt lgkmcnt(0)
	v_fma_f32 v144, v117, v203, v121
	v_fma_f32 v143, v141, v185, v144
	v_fma_f32 v142, v149, v184, v143
	v_mul_f32_e32 v143, 0xbfb8aa3b, v142
	v_exp_f32_e32 v143, v143
	v_mov_b32_e32 v149, v140
	v_mov_b32_e32 v182, v132
	v_mov_b32_e32 v180, v131
	v_add_f32_e32 v143, 1.0, v143
	v_rcp_f32_e32 v143, v143
	v_mov_b32_e32 v178, v130
	v_mul_f32_e32 v142, v142, v143
	v_mul_f32_e32 v144, v137, v142
	v_fma_f32 v137, v116, v202, v120
	v_fma_f32 v137, v149, v183, v137
	v_fma_f32 v137, v148, v182, v137
	v_mul_f32_e32 v142, 0xbfb8aa3b, v137
	v_exp_f32_e32 v142, v142
	v_fma_f32 v143, v115, v201, v119
	v_add_f32_e32 v142, 1.0, v142
	v_rcp_f32_e32 v142, v142
	s_nop 0
	v_mul_f32_e32 v137, v137, v142
	v_mul_f32_e32 v142, v136, v137
	v_mov_b32_e32 v136, v147
	v_mov_b32_e32 v147, v138
	v_fma_f32 v137, v139, v181, v143
	v_fma_f32 v136, v136, v180, v137
	v_mul_f32_e32 v137, 0xbfb8aa3b, v136
	v_exp_f32_e32 v137, v137
	v_fma_f32 v143, v114, v163, v118
	v_add_f32_e32 v137, 1.0, v137
	v_rcp_f32_e32 v137, v137
	s_nop 0
	v_mul_f32_e32 v136, v136, v137
	v_mul_f32_e32 v135, v135, v136
	s_nop 0
	v_fma_f32 v137, v147, v179, v143
	v_fma_f32 v136, v146, v178, v137
	v_mul_f32_e32 v137, 0xbfb8aa3b, v136
	v_exp_f32_e32 v137, v137
	s_nop 0
	v_add_f32_e32 v137, 1.0, v137
	v_rcp_f32_e32 v137, v137
	s_nop 0
	v_mul_f32_e32 v136, v136, v137
	v_mul_f32_e32 v134, v134, v136
	v_mov_b64_e32 v[136:137], s[48:49]
	v_mad_i64_i32 v[136:137], s[12:13], v160, s17, v[136:137]
	v_cvt_pk_bf16_f32 v134, v134, v135
	v_cvt_pk_bf16_f32 v135, v142, v144
	v_lshl_add_u64 v[136:137], v[156:157], 1, v[136:137]
	v_mov_b32_e32 v220, v134
	v_mov_b32_e32 v221, v135

; __device__ __forceinline__ unsigned cvt_pk_bf16(float lo, float hi) { unsigned r; asm volatile("v_cvt_pk_bf16_f32 %0, %1, %2" : "=v"(r) : "v"(lo), "v"(hi)); return r; }
;     __device__ __forceinline__ void operator()(const f32x4 (&acc)[2][2][4][2], const Unit& u, int wr, int wc, int fr, int fq) const {
;     ...
;             for (int m = 0; m < 4; ++m) rs[ai][m] = __builtin_amdgcn_rsqf((float)ss[u.pm * BM + ai * HALF + wr * 64 + m * 16 + fr] * (1.f / (2048.f * 262144.f)) + 1e-6f);
; #pragma unroll
;         for (int n = 0; n < 2; ++n) {
;             const int cbase = 128 * u.pn + 32 * wc + 16 * n + 4 * fq;
;             const f32x4 w0 = *(const f32x4*)(cw + cbase), w1 = *(const f32x4*)(cw + FF + cbase), w2 = *(const f32x4*)(cw + 2 * FF + cbase), b4 = *(const f32x4*)(cb + cbase);
; #pragma unroll
;             for (int ai = 0; ai < 2; ++ai) {
;                 const int slab = u.pm * 4 + 2 * ai + wr;
;                 f32x4 r1p = (f32x4){0.f, 0.f, 0.f, 0.f}, r2p = (f32x4){0.f, 0.f, 0.f, 0.f};
; #pragma unroll
;                 for (int m = 0; m < 4; ++m) {
;                     const f32x4 g = acc[ai][1][m][n] * rs[ai][m], v = acc[ai][0][m][n] * rs[ai][m];
;                     f32x4 r1, r2, a;
; #pragma unroll
;                     for (int e = 0; e < 4; ++e) { r1[e] = __shfl(g[e], src1); r2[e] = __shfl(g[e], src2); }
; #pragma unroll
;                     for (int e = 0; e < 4; ++e) {
;                         const float p1 = fr >= 1 ? r1[e] : r1p[e], p2 = fr >= 2 ? r2[e] : r2p[e];
;                         const float gg = b4[e] + w0[e] * p2 + w1[e] * p1 + w2[e] * g[e];
;                         a[e] = gg * __builtin_amdgcn_rcpf(1.f + __expf(-gg)) * v[e];
;                     }
;                     r1p = r1; r2p = r2;
;                     const size_t row = (size_t)(u.pm * BM + ai * HALF + wr * 64 + m * 16 + fr);
;                     if (m == 0 && fr < 2) {
;                         *(f32x4*)(GF + (size_t)(slab * 2 + fr) * FF + cbase) = g; *(f32x4*)(VF + (size_t)(slab * 2 + fr) * FF + cbase) = v;
;                     } else {
;                         typedef unsigned u32x2v __attribute__((ext_vector_type(2)));
;                         u32x2v w; w.x = cvt_pk_bf16(a[0], a[1]); w.y = cvt_pk_bf16(a[2], a[3]);
;                         *(u32x2v*)(ACT + row * FF + cbase) = w;
.Lalign_up:
	s_nop 0
	v_ffbh_u32_e32 v134, v191
	v_min_u32_e32 v136, 32, v134
	v_lshlrev_b64 v[134:135], v136, v[190:191]
	v_min_u32_e32 v134, 1, v134
	v_or_b32_e32 v134, v135, v134
	v_cvt_f32_u32_e32 v134, v134
	v_ffbh_u32_e32 v135, v189
	v_sub_u32_e32 v136, 32, v136
	v_min_u32_e32 v143, 32, v135
	v_ldexp_f32 v134, v134, v136
	v_fmamk_f32 v136, v134, 0x31000000, v232
	v_lshlrev_b64 v[134:135], v143, v[188:189]
	v_min_u32_e32 v134, 1, v134
	v_or_b32_e32 v134, v135, v134
	v_cvt_f32_u32_e32 v134, v134
	v_sub_u32_e32 v135, 32, v143
	v_rsq_f32_e32 v142, v136
	v_mov_b32_e32 v149, v141
	v_ldexp_f32 v134, v134, v135
	v_fmamk_f32 v136, v134, 0x31000000, v232
	v_ffbh_u32_e32 v134, v187
	v_min_u32_e32 v143, 32, v134
	v_lshlrev_b64 v[134:135], v143, v[186:187]
	v_min_u32_e32 v134, 1, v134
	v_or_b32_e32 v134, v135, v134
	v_cvt_f32_u32_e32 v134, v134
	v_sub_u32_e32 v143, 32, v143
	s_movk_i32 s10, 0x5600
	v_rsq_f32_e32 v136, v136
	v_ldexp_f32 v134, v134, v143
	v_add_u32_e32 v143, s12, v197
	v_pk_mul_f32 v[128:129], v[128:129], v[142:143] op_sel_hi:[1,0]
	s_nop 1
	v_mov_b32_dpp v186, v129 row_ror:1 row_mask:0xf bank_mask:0xf
	v_mov_b32_dpp v191, v129 row_ror:2 row_mask:0xf bank_mask:0xf
	v_mov_b32_e32 v148, v129
	v_pk_mul_f32 v[126:127], v[126:127], v[142:143] op_sel_hi:[1,0]
	v_mad_i64_i32 v[146:147], s[10:11], v143, s10, 0
	s_waitcnt lgkmcnt(1)
	v_cndmask_b32_e64 v185, v186, v185, s[40:41]
	s_waitcnt lgkmcnt(0)
	v_cndmask_b32_e64 v129, v203, v191, s[42:43]
	v_fma_f32 v129, v117, v129, v121
	v_fma_f32 v129, v149, v185, v129
	v_fma_f32 v148, v148, v184, v129
	v_mul_f32_e32 v129, 0xbfb8aa3b, v148
	v_exp_f32_e32 v129, v129
	v_mov_b32_dpp v149, v128 row_ror:1 row_mask:0xf bank_mask:0xf
	v_mov_b32_dpp v203, v128 row_ror:2 row_mask:0xf bank_mask:0xf
	v_mov_b32_dpp v143, v126 row_ror:1 row_mask:0xf bank_mask:0xf
	v_add_f32_e32 v129, 1.0, v129
	v_rcp_f32_e32 v185, v129
	s_waitcnt lgkmcnt(2)
	v_cndmask_b32_e64 v183, v149, v183, s[40:41]
	v_mov_b32_e32 v129, v140
	v_pk_mul_f32 v[128:129], v[128:129], v[182:183]
	s_waitcnt lgkmcnt(1)
	v_cndmask_b32_e64 v183, v202, v203, s[42:43]
	v_fma_f32 v183, v116, v183, v120
	v_add_f32_e32 v129, v129, v183
	v_add_f32_e32 v183, v128, v129
	v_mul_f32_e32 v128, 0xbfb8aa3b, v183
	v_mov_b32_dpp v189, v127 row_ror:1 row_mask:0xf bank_mask:0xf
	v_mov_b32_dpp v190, v127 row_ror:2 row_mask:0xf bank_mask:0xf
	v_exp_f32_e32 v128, v128
	s_waitcnt lgkmcnt(2)
	v_pk_mul_f32 v[124:125], v[124:125], v[142:143] op_sel_hi:[1,0]
	v_mul_f32_e32 v129, v148, v185
	v_mov_b32_dpp v187, v126 row_ror:2 row_mask:0xf bank_mask:0xf
	v_add_f32_e32 v128, 1.0, v128
	v_mul_f32_e32 v125, v125, v129
	v_rcp_f32_e32 v148, v128
	s_waitcnt lgkmcnt(2)
	v_cndmask_b32_e64 v181, v189, v181, s[40:41]
	v_mov_b32_e32 v128, v127
	s_waitcnt lgkmcnt(1)
	v_cndmask_b32_e64 v127, v201, v190, s[42:43]
	v_fma_f32 v127, v115, v127, v119
	v_fma_f32 v127, v139, v181, v127
	v_fma_f32 v128, v128, v180, v127
	v_mul_f32_e32 v127, 0xbfb8aa3b, v128
	v_exp_f32_e32 v129, v127
	v_cndmask_b32_e64 v179, v143, v179, s[40:41]
	s_waitcnt lgkmcnt(0)
	v_cndmask_b32_e64 v163, v163, v187, s[42:43]
	v_fma_f32 v163, v114, v163, v118
	v_fma_f32 v127, v138, v179, v163
	v_fma_f32 v126, v126, v178, v127
	v_mul_f32_e32 v127, 0xbfb8aa3b, v126
	v_exp_f32_e32 v127, v127
	v_add_f32_e32 v129, 1.0, v129
	v_rcp_f32_e32 v129, v129
	v_or_b32_e32 v137, 16, v160
	v_add_f32_e32 v127, 1.0, v127
	v_rcp_f32_e32 v127, v127
	v_mul_f32_e32 v148, v183, v148
	v_pk_mul_f32 v[112:113], v[112:113], v[136:137] op_sel_hi:[1,0]
	v_mul_f32_e32 v124, v124, v148
	s_nop 1
	v_mov_b32_dpp v148, v113 row_ror:1 row_mask:0xf bank_mask:0xf
	v_mov_b32_dpp v204, v113 row_ror:2 row_mask:0xf bank_mask:0xf
	v_pk_mul_f32 v[122:123], v[122:123], v[142:143] op_sel_hi:[1,0]
	v_mul_f32_e32 v128, v128, v129
	v_mul_f32_e32 v126, v126, v127
	v_mul_f32_e32 v123, v123, v128
	v_mul_f32_e32 v122, v122, v126
	v_mov_b64_e32 v[128:129], s[48:49]
	v_cvt_pk_bf16_f32 v126, v122, v123
	v_cvt_pk_bf16_f32 v127, v124, v125
	v_mad_i64_i32 v[122:123], s[10:11], v137, s17, v[128:129]
	v_lshlrev_b64 v[124:125], 1, v[156:157]
	v_lshl_add_u64 v[122:123], v[122:123], 0, v[124:125]
	v_mov_b32_e32 v206, v126
	v_mov_b32_e32 v207, v127
	s_waitcnt lgkmcnt(1)
	v_cndmask_b32_e64 v185, v148, v186, s[40:41]
	v_mov_b32_e32 v126, v113
	v_mov_b32_e32 v127, v141
	s_waitcnt lgkmcnt(0)
	v_cndmask_b32_e64 v113, v191, v204, s[42:43]
	v_fma_f32 v113, v117, v113, v121
	v_fma_f32 v113, v127, v185, v113
	v_fma_f32 v126, v126, v184, v113
	v_mul_f32_e32 v113, 0xbfb8aa3b, v126
	v_exp_f32_e32 v113, v113
	v_mov_b32_dpp v127, v112 row_ror:1 row_mask:0xf bank_mask:0xf
	v_mov_b32_dpp v186, v112 row_ror:2 row_mask:0xf bank_mask:0xf
	v_pk_mul_f32 v[110:111], v[110:111], v[136:137] op_sel_hi:[1,0]
	v_add_f32_e32 v113, 1.0, v113
	v_rcp_f32_e32 v179, v113
	s_waitcnt lgkmcnt(1)
	v_cndmask_b32_e64 v183, v127, v149, s[40:41]
	s_waitcnt lgkmcnt(0)
;     __device__ __forceinline__ void operator()(const f32x4 (&acc)[2][2][4][2], const Unit& u, int wr, int wc, int fr, int fq) const {
;     ...
;             for (int m = 0; m < 4; ++m) rs[ai][m] = __builtin_amdgcn_rsqf((float)ss[u.pm * BM + ai * HALF + wr * 64 + m * 16 + fr] * (1.f / (2048.f * 262144.f)) + 1e-6f);
; #pragma unroll
;         for (int n = 0; n < 2; ++n) {
;             const int cbase = 128 * u.pn + 32 * wc + 16 * n + 4 * fq;
;             const f32x4 w0 = *(const f32x4*)(cw + cbase), w1 = *(const f32x4*)(cw + FF + cbase), w2 = *(const f32x4*)(cw + 2 * FF + cbase), b4 = *(const f32x4*)(cb + cbase);
; #pragma unroll
;             for (int ai = 0; ai < 2; ++ai) {
;                 const int slab = u.pm * 4 + 2 * ai + wr;
;                 f32x4 r1p = (f32x4){0.f, 0.f, 0.f, 0.f}, r2p = (f32x4){0.f, 0.f, 0.f, 0.f};
; #pragma unroll
;                 for (int m = 0; m < 4; ++m) {
;                     const f32x4 g = acc[ai][1][m][n] * rs[ai][m], v = acc[ai][0][m][n] * rs[ai][m];
;                     f32x4 r1, r2, a;
; #pragma unroll
;                     for (int e = 0; e < 4; ++e) { r1[e] = __shfl(g[e], src1); r2[e] = __shfl(g[e], src2); }
; #pragma unroll
;                     for (int e = 0; e < 4; ++e) {
;                         const float p1 = fr >= 1 ? r1[e] : r1p[e], p2 = fr >= 2 ? r2[e] : r2p[e];
;                         const float gg = b4[e] + w0[e] * p2 + w1[e] * p1 + w2[e] * g[e];
;                         a[e] = gg * __builtin_amdgcn_rcpf(1.f + __expf(-gg)) * v[e];
;                     }
;                     r1p = r1; r2p = r2;
;                     const size_t row = (size_t)(u.pm * BM + ai * HALF + wr * 64 + m * 16 + fr);
;                     if (m == 0 && fr < 2) {
;                         *(f32x4*)(GF + (size_t)(slab * 2 + fr) * FF + cbase) = g; *(f32x4*)(VF + (size_t)(slab * 2 + fr) * FF + cbase) = v;
;                     } else {
;                         typedef unsigned u32x2v __attribute__((ext_vector_type(2)));
;                         u32x2v w; w.x = cvt_pk_bf16(a[0], a[1]); w.y = cvt_pk_bf16(a[2], a[3]);
;                         *(u32x2v*)(ACT + row * FF + cbase) = w;
;                     }
;                     if (m == 3 && fr >= 14) *(f32x4*)(GL + (size_t)(slab * 2 + fr - 14) * FF + cbase) = g;
	v_cndmask_b32_e64 v149, v203, v186, s[42:43]
	v_fma_f32 v149, v116, v149, v120
	v_fma_f32 v113, v140, v183, v149
	v_fma_f32 v149, v112, v182, v113
	v_mov_b32_dpp v137, v110 row_ror:1 row_mask:0xf bank_mask:0xf
	v_mul_f32_e32 v112, 0xbfb8aa3b, v149
	v_mov_b32_dpp v201, v111 row_ror:1 row_mask:0xf bank_mask:0xf
	v_mov_b32_dpp v202, v111 row_ror:2 row_mask:0xf bank_mask:0xf
	v_exp_f32_e32 v112, v112
	s_waitcnt lgkmcnt(2)
	v_pk_mul_f32 v[108:109], v[108:109], v[136:137] op_sel_hi:[1,0]
	v_mul_f32_e32 v113, v126, v179
	v_mov_b32_dpp v163, v110 row_ror:2 row_mask:0xf bank_mask:0xf
	v_add_f32_e32 v112, 1.0, v112
	v_mul_f32_e32 v109, v109, v113
	v_rcp_f32_e32 v126, v112
	s_waitcnt lgkmcnt(2)
	v_cndmask_b32_e64 v181, v201, v189, s[40:41]
	v_mov_b32_e32 v112, v111
	s_waitcnt lgkmcnt(1)
	v_cndmask_b32_e64 v111, v190, v202, s[42:43]
	v_fma_f32 v111, v115, v111, v119
	v_fma_f32 v111, v139, v181, v111
	v_fma_f32 v112, v112, v180, v111
	v_mul_f32_e32 v111, 0xbfb8aa3b, v112
	v_exp_f32_e32 v113, v111
	v_cndmask_b32_e64 v179, v137, v143, s[40:41]
	s_waitcnt lgkmcnt(0)
	v_cndmask_b32_e64 v143, v187, v163, s[42:43]
	v_fma_f32 v143, v114, v143, v118
	v_fma_f32 v111, v138, v179, v143
	v_fma_f32 v110, v110, v178, v111
	v_mul_f32_e32 v111, 0xbfb8aa3b, v110
	v_exp_f32_e32 v111, v111
	v_add_f32_e32 v113, 1.0, v113
	v_rcp_f32_e32 v113, v113
	v_fmamk_f32 v134, v134, 0x31000000, v232
	v_add_f32_e32 v111, 1.0, v111
	v_rcp_f32_e32 v111, v111
	v_rsq_f32_e32 v134, v134
	v_pk_mul_f32 v[106:107], v[106:107], v[136:137] op_sel_hi:[1,0]
	v_mul_f32_e32 v126, v149, v126
	v_mul_f32_e32 v112, v112, v113
	v_mul_f32_e32 v110, v110, v111
	v_or_b32_e32 v188, 32, v160
	v_mul_f32_e32 v108, v108, v126
	v_mul_f32_e32 v107, v107, v112
	v_mul_f32_e32 v106, v106, v110
	v_or_b32_e32 v135, 48, v160
	v_cvt_pk_bf16_f32 v106, v106, v107
	v_cvt_pk_bf16_f32 v107, v108, v109
	v_mad_i64_i32 v[108:109], s[10:11], v188, s17, v[128:129]
	v_lshl_add_u64 v[108:109], v[108:109], 0, v[124:125]
	v_pk_mul_f32 v[104:105], v[104:105], v[134:135] op_sel_hi:[1,0]
	v_mov_b32_e32 v208, v106
	v_mov_b32_e32 v209, v107
	v_mov_b32_dpp v106, v105 row_ror:1 row_mask:0xf bank_mask:0xf
	v_mov_b32_dpp v126, v105 row_ror:2 row_mask:0xf bank_mask:0xf
	v_mov_b32_dpp v143, v104 row_ror:2 row_mask:0xf bank_mask:0xf
	v_pk_mul_f32 v[102:103], v[102:103], v[134:135] op_sel_hi:[1,0]
	s_waitcnt lgkmcnt(2)
	v_cndmask_b32_e64 v185, v106, v148, s[40:41]
	s_waitcnt lgkmcnt(1)
	v_cndmask_b32_e64 v126, v204, v126, s[42:43]
	v_fma_f32 v126, v117, v126, v121
	v_fma_f32 v107, v141, v185, v126
	v_fma_f32 v126, v105, v184, v107
	v_mul_f32_e32 v106, 0xbfb8aa3b, v126
	v_exp_f32_e32 v106, v106
	v_mov_b32_dpp v107, v104 row_ror:1 row_mask:0xf bank_mask:0xf
	v_mov_b32_dpp v112, v103 row_ror:1 row_mask:0xf bank_mask:0xf
	v_mov_b32_dpp v113, v103 row_ror:2 row_mask:0xf bank_mask:0xf
	v_add_f32_e32 v106, 1.0, v106
	v_rcp_f32_e32 v148, v106
	s_waitcnt lgkmcnt(2)
	v_cndmask_b32_e64 v183, v107, v127, s[40:41]
	v_cndmask_b32_e64 v127, v186, v143, s[42:43]
	v_fma_f32 v127, v116, v127, v120
	v_fma_f32 v107, v140, v183, v127
	v_fma_f32 v127, v104, v182, v107
	v_mul_f32_e32 v106, 0xbfb8aa3b, v127
	v_exp_f32_e32 v106, v106
	v_pk_mul_f32 v[100:101], v[100:101], v[134:135] op_sel_hi:[1,0]
	v_mul_f32_e32 v107, v126, v148
	v_mov_b32_dpp v110, v102 row_ror:1 row_mask:0xf bank_mask:0xf
	v_add_f32_e32 v106, 1.0, v106
	v_mov_b32_dpp v111, v102 row_ror:2 row_mask:0xf bank_mask:0xf
	v_mul_f32_e32 v101, v101, v107
	v_rcp_f32_e32 v126, v106
	s_waitcnt lgkmcnt(3)
	v_cndmask_b32_e64 v181, v112, v201, s[40:41]
	s_waitcnt lgkmcnt(2)
	v_cndmask_b32_e64 v112, v202, v113, s[42:43]
	v_fma_f32 v112, v115, v112, v119
	v_fma_f32 v107, v139, v181, v112
	v_fma_f32 v112, v103, v180, v107
	v_mul_f32_e32 v106, 0xbfb8aa3b, v112
	v_exp_f32_e32 v113, v106
	s_waitcnt lgkmcnt(1)
	v_cndmask_b32_e64 v179, v110, v137, s[40:41]
	s_waitcnt lgkmcnt(0)
	v_cndmask_b32_e64 v110, v163, v111, s[42:43]
	v_fma_f32 v110, v114, v110, v118
	v_fma_f32 v107, v138, v179, v110
	v_fma_f32 v106, v102, v178, v107
	v_mul_f32_e32 v107, 0xbfb8aa3b, v106
	v_exp_f32_e32 v107, v107
	v_add_f32_e32 v111, 1.0, v113
	v_rcp_f32_e32 v111, v111
	v_mul_f32_e32 v110, v127, v126
	v_add_f32_e32 v107, 1.0, v107
	v_rcp_f32_e32 v107, v107
	v_pk_mul_f32 v[98:99], v[98:99], v[134:135] op_sel_hi:[1,0]
	v_mul_f32_e32 v100, v100, v110
	v_mul_f32_e32 v110, v112, v111
	v_mul_f32_e32 v106, v106, v107
	v_mul_f32_e32 v99, v99, v110
	v_mul_f32_e32 v98, v98, v106
	v_cvt_pk_bf16_f32 v98, v98, v99
	v_cvt_pk_bf16_f32 v99, v100, v101
	v_mad_i64_i32 v[100:101], s[10:11], v135, s17, v[128:129]
	v_readlane_b32 s10, v254, 44
	v_lshl_add_u64 v[110:111], v[100:101], 0, v[124:125]
	v_readlane_b32 s11, v254, 45
	v_mov_b32_e32 v210, v98
	v_mov_b32_e32 v211, v99
	s_nop 0
	v_lshl_add_u64 v[98:99], s[10:11], 0, v[146:147]
	v_lshl_add_u64 v[106:107], v[156:157], 2, v[98:99]
	s_and_saveexec_b64 s[10:11], s[44:45]
	v_readlane_b32 s85, v254, 57
	v_readlane_b32 s93, v254, 58
	s_cbranch_execz .LBB0_47
	global_store_dwordx4 v[106:107], v[102:105], off

; __device__ __forceinline__ unsigned cvt_pk_bf16(float lo, float hi) { unsigned r; asm volatile("v_cvt_pk_bf16_f32 %0, %1, %2" : "=v"(r) : "v"(lo), "v"(hi)); return r; }
;     __device__ __forceinline__ void operator()(const f32x4 (&acc)[2][2][4][2], const Unit& u, int wr, int wc, int fr, int fq) const {
;     ...
;             for (int m = 0; m < 4; ++m) rs[ai][m] = __builtin_amdgcn_rsqf((float)ss[u.pm * BM + ai * HALF + wr * 64 + m * 16 + fr] * (1.f / (2048.f * 262144.f)) + 1e-6f);
; #pragma unroll
;         for (int n = 0; n < 2; ++n) {
;             const int cbase = 128 * u.pn + 32 * wc + 16 * n + 4 * fq;
;             const f32x4 w0 = *(const f32x4*)(cw + cbase), w1 = *(const f32x4*)(cw + FF + cbase), w2 = *(const f32x4*)(cw + 2 * FF + cbase), b4 = *(const f32x4*)(cb + cbase);
; #pragma unroll
;             for (int ai = 0; ai < 2; ++ai) {
;                 const int slab = u.pm * 4 + 2 * ai + wr;
;                 f32x4 r1p = (f32x4){0.f, 0.f, 0.f, 0.f}, r2p = (f32x4){0.f, 0.f, 0.f, 0.f};
; #pragma unroll
;                 for (int m = 0; m < 4; ++m) {
;                     const f32x4 g = acc[ai][1][m][n] * rs[ai][m], v = acc[ai][0][m][n] * rs[ai][m];
;                     f32x4 r1, r2, a;
; #pragma unroll
;                     for (int e = 0; e < 4; ++e) { r1[e] = __shfl(g[e], src1); r2[e] = __shfl(g[e], src2); }
; #pragma unroll
;                     for (int e = 0; e < 4; ++e) {
;                         const float p1 = fr >= 1 ? r1[e] : r1p[e], p2 = fr >= 2 ? r2[e] : r2p[e];
;                         const float gg = b4[e] + w0[e] * p2 + w1[e] * p1 + w2[e] * g[e];
;                         a[e] = gg * __builtin_amdgcn_rcpf(1.f + __expf(-gg)) * v[e];
;                     }
;                     r1p = r1; r2p = r2;
;                     const size_t row = (size_t)(u.pm * BM + ai * HALF + wr * 64 + m * 16 + fr);
;                     if (m == 0 && fr < 2) {
;                         *(f32x4*)(GF + (size_t)(slab * 2 + fr) * FF + cbase) = g; *(f32x4*)(VF + (size_t)(slab * 2 + fr) * FF + cbase) = v;
;                     } else {
;                         typedef unsigned u32x2v __attribute__((ext_vector_type(2)));
;                         u32x2v w; w.x = cvt_pk_bf16(a[0], a[1]); w.y = cvt_pk_bf16(a[2], a[3]);
;                         *(u32x2v*)(ACT + row * FF + cbase) = w;
.LBB0_51:
	s_or_b64 exec, exec, s[10:11]
	s_nop 0
	v_ffbh_u32_e32 v90, v175
	v_min_u32_e32 v93, 32, v90
	v_lshlrev_b64 v[90:91], v93, v[174:175]
	v_min_u32_e32 v90, 1, v90
	v_or_b32_e32 v90, v91, v90
	v_cvt_f32_u32_e32 v90, v90
	v_sub_u32_e32 v91, 32, v93
	v_add_u32_e32 v92, s12, v197
	s_movk_i32 s10, 0x5600
	v_ldexp_f32 v90, v90, v91
	v_mad_i64_i32 v[100:101], s[10:11], v92, s10, 0
	v_fmamk_f32 v92, v90, 0x31000000, v232
	v_rsq_f32_e32 v94, v92
	v_add_u32_e32 v95, 0x90, v160
	v_ffbh_u32_e32 v90, v173
	v_min_u32_e32 v93, 32, v90
	v_pk_mul_f32 v[88:89], v[88:89], v[94:95] op_sel_hi:[1,0]
	s_nop 1
	v_mov_b32_dpp v131, v89 row_ror:1 row_mask:0xf bank_mask:0xf
	v_mov_b32_dpp v138, v89 row_ror:2 row_mask:0xf bank_mask:0xf
	v_mov_b32_e32 v96, v89
	v_lshlrev_b64 v[90:91], v93, v[172:173]
	v_min_u32_e32 v90, 1, v90
	s_waitcnt lgkmcnt(1)
	v_cndmask_b32_e64 v97, v131, v179, s[40:41]
	s_waitcnt lgkmcnt(0)
	v_cndmask_b32_e64 v89, v181, v138, s[42:43]
	v_fma_f32 v89, v117, v89, v121
	v_fma_f32 v89, v127, v97, v89
	v_fma_f32 v96, v126, v96, v89
	v_mul_f32_e32 v89, 0xbfb8aa3b, v96
	v_or_b32_e32 v90, v91, v90
	v_exp_f32_e32 v89, v89
	v_mov_b32_dpp v97, v88 row_ror:1 row_mask:0xf bank_mask:0xf
	v_mov_b32_dpp v140, v88 row_ror:2 row_mask:0xf bank_mask:0xf
	v_cvt_f32_u32_e32 v90, v90
	v_sub_u32_e32 v91, 32, v93
	v_add_f32_e32 v89, 1.0, v89
	v_rcp_f32_e32 v98, v89
	v_ldexp_f32 v90, v90, v91
	s_waitcnt lgkmcnt(1)
	v_cndmask_b32_e64 v89, v97, v163, s[40:41]
	s_waitcnt lgkmcnt(0)
	v_cndmask_b32_e64 v99, v143, v140, s[42:43]
	v_fmamk_f32 v92, v90, 0x31000000, v232
	v_ffbh_u32_e32 v90, v171
	v_fma_f32 v99, v116, v99, v120
	v_min_u32_e32 v93, 32, v90
	v_fma_f32 v89, v149, v89, v99
	v_lshlrev_b64 v[90:91], v93, v[170:171]
	v_fma_f32 v99, v148, v88, v89
	v_min_u32_e32 v90, 1, v90
	v_pk_mul_f32 v[86:87], v[86:87], v[94:95] op_sel_hi:[1,0]
	v_mul_f32_e32 v88, 0xbfb8aa3b, v99
	v_or_b32_e32 v90, v91, v90
	v_mov_b32_dpp v133, v87 row_ror:1 row_mask:0xf bank_mask:0xf
	v_mov_b32_dpp v139, v87 row_ror:2 row_mask:0xf bank_mask:0xf
	v_exp_f32_e32 v88, v88
	v_cvt_f32_u32_e32 v90, v90
	v_sub_u32_e32 v93, 32, v93
	v_pk_mul_f32 v[84:85], v[84:85], v[94:95] op_sel_hi:[1,0]
	v_mul_f32_e32 v89, v96, v98
	v_add_f32_e32 v88, 1.0, v88
	v_ldexp_f32 v90, v90, v93
	v_mov_b32_dpp v93, v86 row_ror:1 row_mask:0xf bank_mask:0xf
	v_mov_b32_dpp v132, v86 row_ror:2 row_mask:0xf bank_mask:0xf
	v_mul_f32_e32 v85, v85, v89
	v_rcp_f32_e32 v96, v88
	s_waitcnt lgkmcnt(3)
	v_cndmask_b32_e64 v89, v133, v177, s[40:41]
	v_mov_b32_e32 v88, v87
	s_waitcnt lgkmcnt(2)
	v_cndmask_b32_e64 v87, v137, v139, s[42:43]
	v_fma_f32 v87, v115, v87, v119
	v_fma_f32 v87, v129, v89, v87
	v_fma_f32 v88, v128, v88, v87
	v_mul_f32_e32 v87, 0xbfb8aa3b, v88
	v_exp_f32_e32 v89, v87
	s_waitcnt lgkmcnt(1)
	v_cndmask_b32_e64 v87, v93, v135, s[40:41]
	s_waitcnt lgkmcnt(0)
	v_cndmask_b32_e64 v98, v103, v132, s[42:43]
	v_fma_f32 v98, v114, v98, v118
	v_fma_f32 v87, v147, v87, v98
	v_fma_f32 v86, v146, v86, v87
	v_mul_f32_e32 v87, 0xbfb8aa3b, v86
	v_exp_f32_e32 v87, v87
	v_add_f32_e32 v89, 1.0, v89
	v_rcp_f32_e32 v89, v89
	v_rsq_f32_e32 v92, v92
	v_add_f32_e32 v87, 1.0, v87
	v_rcp_f32_e32 v87, v87
	v_pk_mul_f32 v[82:83], v[82:83], v[94:95] op_sel_hi:[1,0]
	v_mul_f32_e32 v96, v99, v96
	v_mul_f32_e32 v88, v88, v89
	v_mul_f32_e32 v86, v86, v87
	v_mul_f32_e32 v84, v84, v96
	v_mul_f32_e32 v83, v83, v88
	v_mul_f32_e32 v82, v82, v86
	v_cvt_pk_bf16_f32 v82, v82, v83
	v_cvt_pk_bf16_f32 v83, v84, v85
	v_mov_b64_e32 v[84:85], s[48:49]
	v_mad_i64_i32 v[86:87], s[10:11], v95, s17, v[84:85]
	v_pk_mul_f32 v[80:81], v[80:81], v[92:93] op_sel_hi:[1,0]
	v_lshl_add_u64 v[98:99], v[86:87], 0, v[124:125]
	s_nop 1
	v_mov_b32_dpp v87, v81 row_ror:1 row_mask:0xf bank_mask:0xf
	v_mov_b32_dpp v95, v81 row_ror:2 row_mask:0xf bank_mask:0xf
	v_mov_b32_e32 v214, v82
	v_mov_b32_e32 v215, v83
	v_mov_b32_e32 v82, v81
	v_pk_mul_f32 v[78:79], v[78:79], v[92:93] op_sel_hi:[1,0]
	s_waitcnt lgkmcnt(1)
	v_cndmask_b32_e64 v83, v87, v131, s[40:41]
	s_waitcnt lgkmcnt(0)
	v_cndmask_b32_e64 v81, v138, v95, s[42:43]
	v_fma_f32 v81, v117, v81, v121
	v_fma_f32 v81, v127, v83, v81
	v_fma_f32 v82, v126, v82, v81
	v_mul_f32_e32 v81, 0xbfb8aa3b, v82
	v_exp_f32_e32 v81, v81
	v_mov_b32_dpp v83, v80 row_ror:1 row_mask:0xf bank_mask:0xf
	v_mov_b32_dpp v131, v80 row_ror:2 row_mask:0xf bank_mask:0xf
	v_mov_b32_dpp v89, v79 row_ror:1 row_mask:0xf bank_mask:0xf
	v_add_f32_e32 v81, 1.0, v81
	v_rcp_f32_e32 v96, v81
	s_waitcnt lgkmcnt(2)
	v_cndmask_b32_e64 v81, v83, v97, s[40:41]
	s_waitcnt lgkmcnt(1)
	v_cndmask_b32_e64 v97, v140, v131, s[42:43]
	v_fma_f32 v97, v116, v97, v120
	v_fma_f32 v81, v149, v81, v97
	v_fma_f32 v97, v148, v80, v81
	v_mul_f32_e32 v80, 0xbfb8aa3b, v97
	v_mov_b32_dpp v103, v79 row_ror:2 row_mask:0xf bank_mask:0xf
	v_exp_f32_e32 v80, v80
	v_pk_mul_f32 v[76:77], v[76:77], v[92:93] op_sel_hi:[1,0]
	v_mul_f32_e32 v81, v82, v96
	v_mov_b32_dpp v86, v78 row_ror:1 row_mask:0xf bank_mask:0xf
	v_add_f32_e32 v80, 1.0, v80
	v_mov_b32_dpp v88, v78 row_ror:2 row_mask:0xf bank_mask:0xf
	v_mul_f32_e32 v77, v77, v81
	v_rcp_f32_e32 v82, v80
	s_waitcnt lgkmcnt(3)
	v_cndmask_b32_e64 v81, v89, v133, s[40:41]
	v_mov_b32_e32 v80, v79
	s_waitcnt lgkmcnt(2)
	v_cndmask_b32_e64 v79, v139, v103, s[42:43]
	v_fma_f32 v79, v115, v79, v119
	v_fma_f32 v79, v129, v81, v79
	v_fma_f32 v80, v128, v80, v79
	v_mul_f32_e32 v79, 0xbfb8aa3b, v80
	v_pk_mul_f32 v[74:75], v[74:75], v[92:93] op_sel_hi:[1,0]
	v_exp_f32_e32 v81, v79
	s_waitcnt lgkmcnt(1)
	v_cndmask_b32_e64 v79, v86, v93, s[40:41]
	s_waitcnt lgkmcnt(0)
;     __device__ __forceinline__ void operator()(const f32x4 (&acc)[2][2][4][2], const Unit& u, int wr, int wc, int fr, int fq) const {
;     ...
;             for (int m = 0; m < 4; ++m) rs[ai][m] = __builtin_amdgcn_rsqf((float)ss[u.pm * BM + ai * HALF + wr * 64 + m * 16 + fr] * (1.f / (2048.f * 262144.f)) + 1e-6f);
; #pragma unroll
;         for (int n = 0; n < 2; ++n) {
;             const int cbase = 128 * u.pn + 32 * wc + 16 * n + 4 * fq;
;             const f32x4 w0 = *(const f32x4*)(cw + cbase), w1 = *(const f32x4*)(cw + FF + cbase), w2 = *(const f32x4*)(cw + 2 * FF + cbase), b4 = *(const f32x4*)(cb + cbase);
; #pragma unroll
;             for (int ai = 0; ai < 2; ++ai) {
;                 const int slab = u.pm * 4 + 2 * ai + wr;
;                 f32x4 r1p = (f32x4){0.f, 0.f, 0.f, 0.f}, r2p = (f32x4){0.f, 0.f, 0.f, 0.f};
; #pragma unroll
;                 for (int m = 0; m < 4; ++m) {
;                     const f32x4 g = acc[ai][1][m][n] * rs[ai][m], v = acc[ai][0][m][n] * rs[ai][m];
;                     f32x4 r1, r2, a;
; #pragma unroll
;                     for (int e = 0; e < 4; ++e) { r1[e] = __shfl(g[e], src1); r2[e] = __shfl(g[e], src2); }
; #pragma unroll
;                     for (int e = 0; e < 4; ++e) {
;                         const float p1 = fr >= 1 ? r1[e] : r1p[e], p2 = fr >= 2 ? r2[e] : r2p[e];
;                         const float gg = b4[e] + w0[e] * p2 + w1[e] * p1 + w2[e] * g[e];
;                         a[e] = gg * __builtin_amdgcn_rcpf(1.f + __expf(-gg)) * v[e];
;                     }
;                     r1p = r1; r2p = r2;
;                     const size_t row = (size_t)(u.pm * BM + ai * HALF + wr * 64 + m * 16 + fr);
;                     if (m == 0 && fr < 2) {
;                         *(f32x4*)(GF + (size_t)(slab * 2 + fr) * FF + cbase) = g; *(f32x4*)(VF + (size_t)(slab * 2 + fr) * FF + cbase) = v;
;                     } else {
;                         typedef unsigned u32x2v __attribute__((ext_vector_type(2)));
;                         u32x2v w; w.x = cvt_pk_bf16(a[0], a[1]); w.y = cvt_pk_bf16(a[2], a[3]);
;                         *(u32x2v*)(ACT + row * FF + cbase) = w;
;                     }
;                     if (m == 3 && fr >= 14) *(f32x4*)(GL + (size_t)(slab * 2 + fr - 14) * FF + cbase) = g;
	v_cndmask_b32_e64 v93, v132, v88, s[42:43]
	v_fma_f32 v93, v114, v93, v118
	v_fma_f32 v79, v147, v79, v93
	v_fma_f32 v78, v146, v78, v79
	v_mul_f32_e32 v79, 0xbfb8aa3b, v78
	v_exp_f32_e32 v79, v79
	v_add_f32_e32 v81, 1.0, v81
	v_rcp_f32_e32 v81, v81
	v_fmamk_f32 v90, v90, 0x31000000, v232
	v_add_f32_e32 v79, 1.0, v79
	v_rcp_f32_e32 v79, v79
	v_rsq_f32_e32 v90, v90
	v_mul_f32_e32 v82, v97, v82
	v_mul_f32_e32 v80, v80, v81
	v_mul_f32_e32 v78, v78, v79
	v_add_u32_e32 v130, 0xa0, v160
	v_mul_f32_e32 v76, v76, v82
	v_mul_f32_e32 v75, v75, v80
	v_mul_f32_e32 v74, v74, v78
	v_add_u32_e32 v91, 0xb0, v160
	v_cvt_pk_bf16_f32 v74, v74, v75
	v_cvt_pk_bf16_f32 v75, v76, v77
	v_mad_i64_i32 v[76:77], s[10:11], v130, s17, v[84:85]
	v_lshl_add_u64 v[96:97], v[76:77], 0, v[124:125]
	v_pk_mul_f32 v[72:73], v[72:73], v[90:91] op_sel_hi:[1,0]
	v_mov_b32_e32 v216, v74
	v_mov_b32_e32 v217, v75
	v_mov_b32_dpp v74, v73 row_ror:1 row_mask:0xf bank_mask:0xf
	v_mov_b32_dpp v79, v73 row_ror:2 row_mask:0xf bank_mask:0xf
	v_mov_b32_dpp v81, v72 row_ror:2 row_mask:0xf bank_mask:0xf
	v_pk_mul_f32 v[70:71], v[70:71], v[90:91] op_sel_hi:[1,0]
	s_nop 1
	v_mov_b32_dpp v78, v71 row_ror:1 row_mask:0xf bank_mask:0xf
	s_waitcnt lgkmcnt(3)
	v_cndmask_b32_e64 v75, v74, v87, s[40:41]
	s_waitcnt lgkmcnt(2)
	v_cndmask_b32_e64 v79, v95, v79, s[42:43]
	v_fma_f32 v79, v117, v79, v121
	v_fma_f32 v75, v127, v75, v79
	v_fma_f32 v79, v126, v73, v75
	v_mul_f32_e32 v74, 0xbfb8aa3b, v79
	v_exp_f32_e32 v74, v74
	v_mov_b32_dpp v75, v72 row_ror:1 row_mask:0xf bank_mask:0xf
	s_waitcnt lgkmcnt(2)
	v_cndmask_b32_e64 v81, v131, v81, s[42:43]
	v_fma_f32 v81, v116, v81, v120
	v_add_f32_e32 v74, 1.0, v74
	v_rcp_f32_e32 v82, v74
	s_waitcnt lgkmcnt(0)
	v_cndmask_b32_e64 v75, v75, v83, s[40:41]
	v_mov_b32_dpp v80, v71 row_ror:2 row_mask:0xf bank_mask:0xf
	v_fma_f32 v75, v149, v75, v81
	v_fma_f32 v81, v148, v72, v75
	v_mul_f32_e32 v74, 0xbfb8aa3b, v81
	v_exp_f32_e32 v74, v74
	v_pk_mul_f32 v[68:69], v[68:69], v[90:91] op_sel_hi:[1,0]
	v_mul_f32_e32 v75, v79, v82
	v_mov_b32_dpp v76, v70 row_ror:1 row_mask:0xf bank_mask:0xf
	v_add_f32_e32 v74, 1.0, v74
	v_mov_b32_dpp v77, v70 row_ror:2 row_mask:0xf bank_mask:0xf
	v_mul_f32_e32 v69, v69, v75
	v_rcp_f32_e32 v79, v74
	v_cndmask_b32_e64 v75, v78, v89, s[40:41]
	s_waitcnt lgkmcnt(2)
	v_cndmask_b32_e64 v78, v103, v80, s[42:43]
	v_fma_f32 v78, v115, v78, v119
	v_fma_f32 v75, v129, v75, v78
	v_fma_f32 v78, v128, v71, v75
	v_mul_f32_e32 v74, 0xbfb8aa3b, v78
	v_exp_f32_e32 v80, v74
	s_waitcnt lgkmcnt(1)
	v_cndmask_b32_e64 v75, v76, v86, s[40:41]
	s_waitcnt lgkmcnt(0)
	v_cndmask_b32_e64 v76, v88, v77, s[42:43]
	v_fmac_f32_e32 v118, v114, v76
	v_fma_f32 v75, v147, v75, v118
	v_fma_f32 v74, v146, v70, v75
	v_mul_f32_e32 v75, 0xbfb8aa3b, v74
	v_exp_f32_e32 v75, v75
	v_add_f32_e32 v77, 1.0, v80
	v_rcp_f32_e32 v77, v77
	v_mul_f32_e32 v76, v81, v79
	v_add_f32_e32 v75, 1.0, v75
	v_rcp_f32_e32 v75, v75
	v_pk_mul_f32 v[66:67], v[66:67], v[90:91] op_sel_hi:[1,0]
	v_mul_f32_e32 v68, v68, v76
	v_mul_f32_e32 v76, v78, v77
	v_mul_f32_e32 v74, v74, v75
	v_mul_f32_e32 v67, v67, v76
	v_mul_f32_e32 v66, v66, v74
	v_cvt_pk_bf16_f32 v66, v66, v67
	v_cvt_pk_bf16_f32 v67, v68, v69
	v_mad_i64_i32 v[68:69], s[10:11], v91, s17, v[84:85]
	v_readlane_b32 s10, v254, 44
	v_lshl_add_u64 v[88:89], v[68:69], 0, v[124:125]
	v_readlane_b32 s11, v254, 45
	v_mov_b32_e32 v218, v66
	v_mov_b32_e32 v219, v67
	s_nop 0
	v_lshl_add_u64 v[66:67], s[10:11], 0, v[100:101]
	v_lshl_add_u64 v[86:87], v[156:157], 2, v[66:67]
	s_and_saveexec_b64 s[10:11], s[44:45]
	s_cbranch_execz .LBB0_53
	global_store_dwordx4 v[86:87], v[70:73], off
.LBB0_53:
	s_or_b64 exec, exec, s[10:11]
	s_nop 0
	v_or_b32_e32 v70, 16, v156
	v_ashrrev_i32_e32 v71, 31, v70
	v_lshlrev_b64 v[70:71], 2, v[70:71]
	v_lshl_add_u64 v[72:73], s[60:61], 0, v[70:71]
	v_lshl_add_u64 v[70:71], s[62:63], 0, v[70:71]
	ds_read_b128 v[66:69], v166 offset:64
	ds_read_b128 v[78:81], v166 offset:576
	ds_read_b128 v[74:77], v166 offset:1088
	s_nop 0
	ds_read_b128 v[70:73], v166 offset:1600
	v_mov_b32_e32 v163, v162
	v_mov_b32_e32 v120, v162
	v_mov_b32_e32 v121, v162
	v_pk_mul_f32 v[84:85], v[60:61], v[120:121]
	v_pk_mul_f32 v[82:83], v[58:59], v[162:163]
	s_nop 1
	v_mov_b32_dpp v101, v82 row_ror:1 row_mask:0xf bank_mask:0xf
	v_mov_b32_dpp v91, v82 row_ror:2 row_mask:0xf bank_mask:0xf
	v_mov_b32_dpp v115, v83 row_ror:1 row_mask:0xf bank_mask:0xf
	v_mov_b32_dpp v93, v83 row_ror:2 row_mask:0xf bank_mask:0xf
	v_mov_b32_dpp v117, v84 row_ror:1 row_mask:0xf bank_mask:0xf
	v_mov_b32_dpp v95, v84 row_ror:2 row_mask:0xf bank_mask:0xf
	v_mov_b32_dpp v119, v85 row_ror:1 row_mask:0xf bank_mask:0xf
	v_mov_b32_dpp v103, v85 row_ror:2 row_mask:0xf bank_mask:0xf
	v_pk_mul_f32 v[60:61], v[64:65], v[120:121]
	v_pk_mul_f32 v[58:59], v[62:63], v[162:163]
	s_and_saveexec_b64 s[10:11], s[42:43]
	s_xor_b64 s[10:11], exec, s[10:11]
	s_cbranch_execz .LBB0_55
	s_waitcnt lgkmcnt(0)
	s_waitcnt lgkmcnt(0)
	v_mov_b32_e32 v118, v77
	s_waitcnt lgkmcnt(1)
	s_waitcnt lgkmcnt(0)
	v_fma_f32 v64, v69, v103, v73
	v_fma_f32 v63, v81, v119, v64
	v_fma_f32 v62, v85, v118, v63
	v_mul_f32_e32 v63, 0xbfb8aa3b, v62
	v_exp_f32_e32 v63, v63
	v_mov_b32_e32 v85, v80
	v_mov_b32_e32 v116, v76
	v_mov_b32_e32 v114, v75
	v_add_f32_e32 v63, 1.0, v63
	v_rcp_f32_e32 v63, v63
	v_mov_b32_e32 v100, v74
	v_mul_f32_e32 v62, v62, v63
	v_mul_f32_e32 v64, v61, v62
	v_fma_f32 v61, v68, v95, v72
	v_fma_f32 v61, v85, v117, v61
	v_fma_f32 v61, v84, v116, v61
	v_mul_f32_e32 v62, 0xbfb8aa3b, v61
	v_exp_f32_e32 v62, v62
	v_fma_f32 v63, v67, v93, v71
	v_add_f32_e32 v62, 1.0, v62
	v_rcp_f32_e32 v62, v62
	s_nop 0
	v_mul_f32_e32 v61, v61, v62
	v_mul_f32_e32 v62, v60, v61
	v_mov_b32_e32 v60, v83
	v_mov_b32_e32 v83, v78
	v_fma_f32 v61, v79, v115, v63
	v_fma_f32 v60, v60, v114, v61
	v_mul_f32_e32 v61, 0xbfb8aa3b, v60
	v_exp_f32_e32 v61, v61
	v_fma_f32 v63, v66, v91, v70
	v_add_f32_e32 v61, 1.0, v61
	v_rcp_f32_e32 v61, v61
	s_nop 0
	v_mul_f32_e32 v60, v60, v61
	v_mul_f32_e32 v59, v59, v60
	s_nop 0
	v_fma_f32 v61, v83, v101, v63
	v_fma_f32 v60, v82, v100, v61
	v_mul_f32_e32 v61, 0xbfb8aa3b, v60
	v_exp_f32_e32 v61, v61
	s_nop 0
	v_add_f32_e32 v61, 1.0, v61
	v_rcp_f32_e32 v61, v61
	s_nop 0
	v_mul_f32_e32 v60, v60, v61
	v_mul_f32_e32 v58, v58, v60
	v_mov_b64_e32 v[60:61], s[48:49]
	v_mad_i64_i32 v[60:61], s[12:13], v160, s17, v[60:61]
	v_cvt_pk_bf16_f32 v58, v58, v59
	v_cvt_pk_bf16_f32 v59, v62, v64
	v_lshl_add_u64 v[60:61], v[156:157], 1, v[60:61]
	v_mov_b32_e32 v64, v77
	v_mov_b32_e32 v62, v75
	s_nop 1
	v_permlane16_swap_b32_e32 v220, v58
	v_permlane16_swap_b32_e32 v221, v59
	v_mov_b32_e32 v222, v58
	v_mov_b32_e32 v223, v59
	v_add_co_u32_e64 v60, s[98:99], v60, v205
	s_nop 1
	v_addc_co_u32_e64 v61, s[98:99], 0, v61, s[98:99]
	global_store_dwordx4 v[60:61], v[220:223], off nt

;     __device__ __forceinline__ void operator()(const f32x4 (&acc)[2][2][4][2], const Unit& u, int wr, int wc, int fr, int fq) const {
;     ...
;             for (int m = 0; m < 4; ++m) rs[ai][m] = __builtin_amdgcn_rsqf((float)ss[u.pm * BM + ai * HALF + wr * 64 + m * 16 + fr] * (1.f / (2048.f * 262144.f)) + 1e-6f);
; #pragma unroll
;         for (int n = 0; n < 2; ++n) {
;             const int cbase = 128 * u.pn + 32 * wc + 16 * n + 4 * fq;
;             const f32x4 w0 = *(const f32x4*)(cw + cbase), w1 = *(const f32x4*)(cw + FF + cbase), w2 = *(const f32x4*)(cw + 2 * FF + cbase), b4 = *(const f32x4*)(cb + cbase);
; #pragma unroll
;             for (int ai = 0; ai < 2; ++ai) {
;                 const int slab = u.pm * 4 + 2 * ai + wr;
;                 f32x4 r1p = (f32x4){0.f, 0.f, 0.f, 0.f}, r2p = (f32x4){0.f, 0.f, 0.f, 0.f};
; #pragma unroll
;                 for (int m = 0; m < 4; ++m) {
;                     const f32x4 g = acc[ai][1][m][n] * rs[ai][m], v = acc[ai][0][m][n] * rs[ai][m];
;                     f32x4 r1, r2, a;
; #pragma unroll
;                     for (int e = 0; e < 4; ++e) { r1[e] = __shfl(g[e], src1); r2[e] = __shfl(g[e], src2); }
; #pragma unroll
;                     for (int e = 0; e < 4; ++e) {
;                         const float p1 = fr >= 1 ? r1[e] : r1p[e], p2 = fr >= 2 ? r2[e] : r2p[e];
;                         const float gg = b4[e] + w0[e] * p2 + w1[e] * p1 + w2[e] * g[e];
;                         a[e] = gg * __builtin_amdgcn_rcpf(1.f + __expf(-gg)) * v[e];
;                     }
;                     r1p = r1; r2p = r2;
;                     const size_t row = (size_t)(u.pm * BM + ai * HALF + wr * 64 + m * 16 + fr);
;                     if (m == 0 && fr < 2) {
;                         *(f32x4*)(GF + (size_t)(slab * 2 + fr) * FF + cbase) = g; *(f32x4*)(VF + (size_t)(slab * 2 + fr) * FF + cbase) = v;
;                     } else {
;                         typedef unsigned u32x2v __attribute__((ext_vector_type(2)));
;                         u32x2v w; w.x = cvt_pk_bf16(a[0], a[1]); w.y = cvt_pk_bf16(a[2], a[3]);
;                         *(u32x2v*)(ACT + row * FF + cbase) = w;
;                     }
;                     if (m == 3 && fr >= 14) *(f32x4*)(GL + (size_t)(slab * 2 + fr - 14) * FF + cbase) = g;
.LBB0_57:
	s_or_b64 exec, exec, s[10:11]
	v_mov_b32_e32 v58, v142
	v_mov_b32_e32 v59, v142
	v_pk_mul_f32 v[56:57], v[56:57], v[58:59]
	s_nop 1
	v_mov_b32_dpp v83, v57 row_ror:1 row_mask:0xf bank_mask:0xf
	v_mov_b32_dpp v114, v57 row_ror:2 row_mask:0xf bank_mask:0xf
	v_mov_b32_e32 v60, v57
	s_waitcnt lgkmcnt(0)
	v_mov_b32_e32 v61, v81
	v_pk_mul_f32 v[52:53], v[52:53], v[58:59]
	s_waitcnt lgkmcnt(1)
	v_cndmask_b32_e64 v65, v83, v119, s[40:41]
	s_waitcnt lgkmcnt(0)
	v_cndmask_b32_e64 v57, v103, v114, s[42:43]
	s_waitcnt lgkmcnt(0)
	v_fma_f32 v57, v69, v57, v73
	v_fma_f32 v57, v61, v65, v57
	v_fma_f32 v60, v60, v64, v57
	v_mul_f32_e32 v57, 0xbfb8aa3b, v60
	v_exp_f32_e32 v57, v57
	v_mov_b32_dpp v61, v56 row_ror:1 row_mask:0xf bank_mask:0xf
	v_mov_b32_dpp v103, v56 row_ror:2 row_mask:0xf bank_mask:0xf
	v_mov_b32_e32 v143, v142
	v_add_f32_e32 v57, 1.0, v57
	v_rcp_f32_e32 v58, v57
	s_waitcnt lgkmcnt(1)
	v_cndmask_b32_e64 v77, v61, v117, s[40:41]
	s_waitcnt lgkmcnt(0)
	v_cndmask_b32_e64 v59, v95, v103, s[42:43]
	v_fma_f32 v59, v68, v59, v72
	v_fma_f32 v57, v80, v77, v59
	v_fma_f32 v59, v56, v76, v57
	v_pk_mul_f32 v[54:55], v[54:55], v[142:143]
	v_mul_f32_e32 v56, 0xbfb8aa3b, v59
	s_nop 1
	v_mov_b32_dpp v85, v55 row_ror:1 row_mask:0xf bank_mask:0xf
	v_mov_b32_dpp v100, v55 row_ror:2 row_mask:0xf bank_mask:0xf
	v_exp_f32_e32 v56, v56
	v_mul_f32_e32 v57, v60, v58
	v_mov_b32_dpp v82, v54 row_ror:1 row_mask:0xf bank_mask:0xf
	v_mov_b32_dpp v84, v54 row_ror:2 row_mask:0xf bank_mask:0xf
	v_add_f32_e32 v56, 1.0, v56
	v_mul_f32_e32 v53, v53, v57
	v_rcp_f32_e32 v58, v56
	s_waitcnt lgkmcnt(3)
	v_cndmask_b32_e64 v63, v85, v115, s[40:41]
	v_mov_b32_e32 v56, v55
	s_waitcnt lgkmcnt(2)
	v_cndmask_b32_e64 v55, v93, v100, s[42:43]
	v_fma_f32 v55, v67, v55, v71
	v_fma_f32 v55, v79, v63, v55
	v_fma_f32 v56, v56, v62, v55
	v_mul_f32_e32 v55, 0xbfb8aa3b, v56
	v_exp_f32_e32 v57, v55
	s_waitcnt lgkmcnt(1)
	v_cndmask_b32_e64 v75, v82, v101, s[40:41]
	s_waitcnt lgkmcnt(0)
	v_cndmask_b32_e64 v60, v91, v84, s[42:43]
	v_fma_f32 v60, v66, v60, v70
	v_fma_f32 v55, v78, v75, v60
	v_fma_f32 v54, v54, v74, v55
	v_mul_f32_e32 v55, 0xbfb8aa3b, v54
	v_exp_f32_e32 v55, v55
	v_add_f32_e32 v57, 1.0, v57
	v_rcp_f32_e32 v57, v57
	v_pk_mul_f32 v[50:51], v[50:51], v[142:143]
	v_add_f32_e32 v55, 1.0, v55
	v_rcp_f32_e32 v55, v55
	v_mul_f32_e32 v56, v56, v57
	v_mul_f32_e32 v58, v59, v58
	v_mul_f32_e32 v51, v51, v56
	v_mul_f32_e32 v54, v54, v55
	v_mul_f32_e32 v50, v50, v54
	v_mul_f32_e32 v52, v52, v58
	v_cvt_pk_bf16_f32 v50, v50, v51
	v_cvt_pk_bf16_f32 v51, v52, v53
	s_nop 1
	v_permlane16_swap_b32_e32 v206, v50
	v_permlane16_swap_b32_e32 v207, v51
	v_mov_b32_e32 v220, v206
	v_mov_b32_e32 v221, v207
	v_mov_b32_e32 v222, v50
	v_mov_b32_e32 v223, v51
	v_add_co_u32_e64 v122, s[98:99], v122, v205
	s_nop 1
	v_addc_co_u32_e64 v123, s[98:99], 0, v123, s[98:99]
	global_store_dwordx4 v[122:123], v[220:223], off nt
	v_mov_b32_e32 v50, v136
	v_mov_b32_e32 v51, v136
	v_pk_mul_f32 v[48:49], v[48:49], v[50:51]
	s_nop 1
	v_mov_b32_dpp v55, v49 row_ror:1 row_mask:0xf bank_mask:0xf
	v_mov_b32_dpp v59, v49 row_ror:2 row_mask:0xf bank_mask:0xf
	v_mov_b32_e32 v52, v49
	v_mov_b32_e32 v53, v81
	v_mov_b32_dpp v60, v48 row_ror:2 row_mask:0xf bank_mask:0xf
	s_waitcnt lgkmcnt(2)
	v_cndmask_b32_e64 v65, v55, v83, s[40:41]
	s_waitcnt lgkmcnt(1)
	v_cndmask_b32_e64 v49, v114, v59, s[42:43]
	v_fma_f32 v49, v69, v49, v73
	v_fma_f32 v49, v53, v65, v49
	v_fma_f32 v52, v52, v64, v49
	v_mul_f32_e32 v49, 0xbfb8aa3b, v52
	v_exp_f32_e32 v49, v49
	v_mov_b32_dpp v53, v48 row_ror:1 row_mask:0xf bank_mask:0xf
	v_pk_mul_f32 v[44:45], v[44:45], v[50:51]
	s_waitcnt lgkmcnt(1)
	v_cndmask_b32_e64 v51, v103, v60, s[42:43]
	v_add_f32_e32 v49, 1.0, v49
	v_rcp_f32_e32 v50, v49
	s_waitcnt lgkmcnt(0)
	v_cndmask_b32_e64 v77, v53, v61, s[40:41]
	v_fma_f32 v51, v68, v51, v72
	v_fma_f32 v49, v80, v77, v51
	v_mov_b32_e32 v137, v136
	v_fma_f32 v51, v48, v76, v49
	v_pk_mul_f32 v[46:47], v[46:47], v[136:137]
	v_mul_f32_e32 v48, 0xbfb8aa3b, v51
	s_nop 1
	v_mov_b32_dpp v57, v47 row_ror:1 row_mask:0xf bank_mask:0xf
	v_mov_b32_dpp v58, v47 row_ror:2 row_mask:0xf bank_mask:0xf
	v_exp_f32_e32 v48, v48
	v_mul_f32_e32 v49, v52, v50
	v_mov_b32_dpp v54, v46 row_ror:1 row_mask:0xf bank_mask:0xf
	v_mov_b32_dpp v56, v46 row_ror:2 row_mask:0xf bank_mask:0xf
	v_add_f32_e32 v48, 1.0, v48
	v_mul_f32_e32 v45, v45, v49
	v_rcp_f32_e32 v50, v48
	s_waitcnt lgkmcnt(3)
	v_cndmask_b32_e64 v63, v57, v85, s[40:41]
	v_mov_b32_e32 v48, v47
	s_waitcnt lgkmcnt(2)
	v_cndmask_b32_e64 v47, v100, v58, s[42:43]
	v_fma_f32 v47, v67, v47, v71
	v_fma_f32 v47, v79, v63, v47
	v_fma_f32 v48, v48, v62, v47
	v_mul_f32_e32 v47, 0xbfb8aa3b, v48
	v_exp_f32_e32 v49, v47
	s_waitcnt lgkmcnt(1)
	v_cndmask_b32_e64 v75, v54, v82, s[40:41]
	s_waitcnt lgkmcnt(0)
	v_cndmask_b32_e64 v52, v84, v56, s[42:43]
	v_fma_f32 v52, v66, v52, v70
	v_fma_f32 v47, v78, v75, v52
	v_fma_f32 v46, v46, v74, v47
	v_mul_f32_e32 v47, 0xbfb8aa3b, v46
	v_exp_f32_e32 v47, v47
	v_add_f32_e32 v49, 1.0, v49
	v_rcp_f32_e32 v49, v49
	v_pk_mul_f32 v[42:43], v[42:43], v[136:137]
	v_add_f32_e32 v47, 1.0, v47
	v_rcp_f32_e32 v47, v47
	v_mul_f32_e32 v48, v48, v49
	v_mul_f32_e32 v50, v51, v50
	v_mul_f32_e32 v43, v43, v48
	v_mul_f32_e32 v46, v46, v47
	v_mul_f32_e32 v42, v42, v46
	v_mul_f32_e32 v44, v44, v50
	v_cvt_pk_bf16_f32 v42, v42, v43
	v_cvt_pk_bf16_f32 v43, v44, v45
	s_nop 1
	v_permlane16_swap_b32_e32 v208, v42
	v_permlane16_swap_b32_e32 v209, v43
	v_mov_b32_e32 v220, v208
	v_mov_b32_e32 v221, v209
	v_mov_b32_e32 v222, v42
	v_mov_b32_e32 v223, v43
	v_add_co_u32_e64 v108, s[98:99], v108, v205
	s_nop 1
	v_addc_co_u32_e64 v109, s[98:99], 0, v109, s[98:99]
	global_store_dwordx4 v[108:109], v[220:223], off nt
	v_mov_b32_e32 v42, v134
	v_mov_b32_e32 v43, v134
	v_pk_mul_f32 v[40:41], v[40:41], v[42:43]
	s_nop 1
	v_mov_b32_dpp v44, v41 row_ror:1 row_mask:0xf bank_mask:0xf
	v_mov_b32_dpp v50, v41 row_ror:2 row_mask:0xf bank_mask:0xf
	v_mov_b32_dpp v51, v40 row_ror:2 row_mask:0xf bank_mask:0xf
	v_pk_mul_f32 v[36:37], v[36:37], v[42:43]
	s_waitcnt lgkmcnt(2)
;     __device__ __forceinline__ void operator()(const f32x4 (&acc)[2][2][4][2], const Unit& u, int wr, int wc, int fr, int fq) const {
;     ...
;             for (int m = 0; m < 4; ++m) rs[ai][m] = __builtin_amdgcn_rsqf((float)ss[u.pm * BM + ai * HALF + wr * 64 + m * 16 + fr] * (1.f / (2048.f * 262144.f)) + 1e-6f);
; #pragma unroll
;         for (int n = 0; n < 2; ++n) {
;             const int cbase = 128 * u.pn + 32 * wc + 16 * n + 4 * fq;
;             const f32x4 w0 = *(const f32x4*)(cw + cbase), w1 = *(const f32x4*)(cw + FF + cbase), w2 = *(const f32x4*)(cw + 2 * FF + cbase), b4 = *(const f32x4*)(cb + cbase);
; #pragma unroll
;             for (int ai = 0; ai < 2; ++ai) {
;                 const int slab = u.pm * 4 + 2 * ai + wr;
;                 f32x4 r1p = (f32x4){0.f, 0.f, 0.f, 0.f}, r2p = (f32x4){0.f, 0.f, 0.f, 0.f};
; #pragma unroll
;                 for (int m = 0; m < 4; ++m) {
;                     const f32x4 g = acc[ai][1][m][n] * rs[ai][m], v = acc[ai][0][m][n] * rs[ai][m];
;                     f32x4 r1, r2, a;
; #pragma unroll
;                     for (int e = 0; e < 4; ++e) { r1[e] = __shfl(g[e], src1); r2[e] = __shfl(g[e], src2); }
; #pragma unroll
;                     for (int e = 0; e < 4; ++e) {
;                         const float p1 = fr >= 1 ? r1[e] : r1p[e], p2 = fr >= 2 ? r2[e] : r2p[e];
;                         const float gg = b4[e] + w0[e] * p2 + w1[e] * p1 + w2[e] * g[e];
;                         a[e] = gg * __builtin_amdgcn_rcpf(1.f + __expf(-gg)) * v[e];
;                     }
;                     r1p = r1; r2p = r2;
;                     const size_t row = (size_t)(u.pm * BM + ai * HALF + wr * 64 + m * 16 + fr);
;                     if (m == 0 && fr < 2) {
;                         *(f32x4*)(GF + (size_t)(slab * 2 + fr) * FF + cbase) = g; *(f32x4*)(VF + (size_t)(slab * 2 + fr) * FF + cbase) = v;
;                     } else {
;                         typedef unsigned u32x2v __attribute__((ext_vector_type(2)));
;                         u32x2v w; w.x = cvt_pk_bf16(a[0], a[1]); w.y = cvt_pk_bf16(a[2], a[3]);
;                         *(u32x2v*)(ACT + row * FF + cbase) = w;
;                     }
;                     if (m == 3 && fr >= 14) *(f32x4*)(GL + (size_t)(slab * 2 + fr - 14) * FF + cbase) = g;
	v_cndmask_b32_e64 v65, v44, v55, s[40:41]
	s_waitcnt lgkmcnt(1)
	v_cndmask_b32_e64 v50, v59, v50, s[42:43]
	v_fma_f32 v50, v69, v50, v73
	v_fma_f32 v45, v81, v65, v50
	v_fma_f32 v44, v41, v64, v45
	v_mul_f32_e32 v45, 0xbfb8aa3b, v44
	v_exp_f32_e32 v45, v45
	v_mov_b32_dpp v50, v40 row_ror:1 row_mask:0xf bank_mask:0xf
	v_mov_b32_e32 v135, v134
	v_add_f32_e32 v42, 1.0, v45
	v_rcp_f32_e32 v45, v42
	s_waitcnt lgkmcnt(0)
	v_cndmask_b32_e64 v77, v50, v53, s[40:41]
	v_cndmask_b32_e64 v50, v60, v51, s[42:43]
	v_fma_f32 v50, v68, v50, v72
	v_fma_f32 v43, v80, v77, v50
	v_fma_f32 v50, v40, v76, v43
	v_pk_mul_f32 v[38:39], v[38:39], v[134:135]
	v_mul_f32_e32 v42, 0xbfb8aa3b, v50
	s_nop 1
	v_mov_b32_dpp v48, v39 row_ror:1 row_mask:0xf bank_mask:0xf
	v_mov_b32_dpp v49, v39 row_ror:2 row_mask:0xf bank_mask:0xf
	v_exp_f32_e32 v42, v42
	v_mul_f32_e32 v43, v44, v45
	v_mov_b32_dpp v46, v38 row_ror:1 row_mask:0xf bank_mask:0xf
	v_mov_b32_dpp v47, v38 row_ror:2 row_mask:0xf bank_mask:0xf
	v_add_f32_e32 v42, 1.0, v42
	v_mul_f32_e32 v37, v37, v43
	v_rcp_f32_e32 v44, v42
	s_waitcnt lgkmcnt(3)
	v_cndmask_b32_e64 v63, v48, v57, s[40:41]
	s_waitcnt lgkmcnt(2)
	v_cndmask_b32_e64 v45, v58, v49, s[42:43]
	v_fma_f32 v45, v67, v45, v71
	v_fma_f32 v43, v79, v63, v45
	v_fma_f32 v45, v39, v62, v43
	v_mul_f32_e32 v42, 0xbfb8aa3b, v45
	v_exp_f32_e32 v48, v42
	s_waitcnt lgkmcnt(1)
	v_cndmask_b32_e64 v75, v46, v54, s[40:41]
	s_waitcnt lgkmcnt(0)
	v_cndmask_b32_e64 v46, v56, v47, s[42:43]
	v_fma_f32 v46, v66, v46, v70
	v_fma_f32 v43, v78, v75, v46
	v_fma_f32 v42, v38, v74, v43
	v_mul_f32_e32 v43, 0xbfb8aa3b, v42
	v_exp_f32_e32 v43, v43
	v_add_f32_e32 v46, 1.0, v48
	v_rcp_f32_e32 v46, v46
	v_mul_f32_e32 v44, v50, v44
	v_add_f32_e32 v43, 1.0, v43
	v_rcp_f32_e32 v43, v43
	v_pk_mul_f32 v[34:35], v[34:35], v[134:135]
	v_mul_f32_e32 v36, v36, v44
	v_mul_f32_e32 v44, v45, v46
	v_mul_f32_e32 v42, v42, v43
	v_mul_f32_e32 v35, v35, v44
	v_mul_f32_e32 v34, v34, v42
	v_cvt_pk_bf16_f32 v34, v34, v35
	v_cvt_pk_bf16_f32 v35, v36, v37
	s_nop 1
	v_permlane16_swap_b32_e32 v210, v34
	v_permlane16_swap_b32_e32 v211, v35
	v_mov_b32_e32 v220, v210
	v_mov_b32_e32 v221, v211
	v_mov_b32_e32 v222, v34
	v_mov_b32_e32 v223, v35
	v_add_co_u32_e64 v110, s[98:99], v110, v205
	s_nop 1
	v_addc_co_u32_e64 v111, s[98:99], 0, v111, s[98:99]
	global_store_dwordx4 v[110:111], v[220:223], off nt
	s_and_saveexec_b64 s[10:11], s[44:45]
	s_cbranch_execz .LBB0_59
	global_store_dwordx4 v[106:107], v[38:41], off offset:64
.LBB0_59:
	s_or_b64 exec, exec, s[10:11]
	v_mov_b32_e32 v103, v102
	v_mov_b32_e32 v42, v102
	v_mov_b32_e32 v43, v102
	v_pk_mul_f32 v[36:37], v[28:29], v[42:43]
	v_pk_mul_f32 v[34:35], v[26:27], v[102:103]
	s_nop 1
	v_mov_b32_dpp v75, v34 row_ror:1 row_mask:0xf bank_mask:0xf
	v_mov_b32_dpp v38, v34 row_ror:2 row_mask:0xf bank_mask:0xf
	v_mov_b32_dpp v63, v35 row_ror:1 row_mask:0xf bank_mask:0xf
	v_mov_b32_dpp v39, v35 row_ror:2 row_mask:0xf bank_mask:0xf
	v_mov_b32_dpp v77, v36 row_ror:1 row_mask:0xf bank_mask:0xf
	v_mov_b32_dpp v40, v36 row_ror:2 row_mask:0xf bank_mask:0xf
	v_mov_b32_dpp v65, v37 row_ror:1 row_mask:0xf bank_mask:0xf
	v_mov_b32_dpp v41, v37 row_ror:2 row_mask:0xf bank_mask:0xf
	v_pk_mul_f32 v[28:29], v[32:33], v[42:43]
	v_pk_mul_f32 v[26:27], v[30:31], v[102:103]
	s_and_saveexec_b64 s[10:11], s[42:43]
	s_xor_b64 s[10:11], exec, s[10:11]
	s_cbranch_execz .LBB0_61
	s_waitcnt lgkmcnt(1)
	s_waitcnt lgkmcnt(0)
	v_fma_f32 v32, v69, v41, v73
	v_fma_f32 v31, v81, v65, v32
	v_fma_f32 v30, v37, v64, v31
	v_mul_f32_e32 v31, 0xbfb8aa3b, v30
	v_exp_f32_e32 v31, v31
	v_mov_b32_e32 v37, v80
	v_add_f32_e32 v31, 1.0, v31
	v_rcp_f32_e32 v31, v31
	s_nop 0
	v_mul_f32_e32 v30, v30, v31
	v_mul_f32_e32 v32, v29, v30
	v_fma_f32 v29, v68, v40, v72
	v_fma_f32 v29, v37, v77, v29
	v_fma_f32 v29, v36, v76, v29
	v_mul_f32_e32 v30, 0xbfb8aa3b, v29
	v_exp_f32_e32 v30, v30
	v_fma_f32 v31, v67, v39, v71
	v_add_f32_e32 v30, 1.0, v30
	v_rcp_f32_e32 v30, v30
	s_nop 0
	v_mul_f32_e32 v29, v29, v30
	v_mul_f32_e32 v30, v28, v29
	v_mov_b32_e32 v28, v35
	v_mov_b32_e32 v35, v78
	v_fma_f32 v29, v79, v63, v31
	v_fma_f32 v28, v28, v62, v29
	v_mul_f32_e32 v29, 0xbfb8aa3b, v28
	v_exp_f32_e32 v29, v29
	v_fma_f32 v31, v66, v38, v70
	v_add_f32_e32 v29, 1.0, v29
	v_rcp_f32_e32 v29, v29
	s_nop 0
	v_mul_f32_e32 v28, v28, v29
	v_mul_f32_e32 v27, v27, v28
	s_nop 0
	v_fma_f32 v29, v35, v75, v31
	v_fma_f32 v28, v34, v74, v29
	v_mul_f32_e32 v29, 0xbfb8aa3b, v28
	v_exp_f32_e32 v29, v29
	s_nop 0
	v_add_f32_e32 v29, 1.0, v29
	v_rcp_f32_e32 v29, v29
	s_nop 0
	v_mul_f32_e32 v28, v28, v29
	v_mul_f32_e32 v26, v26, v28
	v_mov_b64_e32 v[28:29], s[48:49]
	v_mad_i64_i32 v[28:29], s[12:13], v180, s17, v[28:29]
	v_cvt_pk_bf16_f32 v26, v26, v27
	v_cvt_pk_bf16_f32 v27, v30, v32
	v_lshl_add_u64 v[28:29], v[156:157], 1, v[28:29]
	s_nop 1
	v_permlane16_swap_b32_e32 v212, v26
	v_permlane16_swap_b32_e32 v213, v27
	v_mov_b32_e32 v220, v212
	v_mov_b32_e32 v221, v213
	v_mov_b32_e32 v222, v26
	v_mov_b32_e32 v223, v27
	v_add_co_u32_e64 v28, s[98:99], v28, v205
	s_nop 1
	v_addc_co_u32_e64 v29, s[98:99], 0, v29, s[98:99]
	global_store_dwordx4 v[28:29], v[220:223], off nt

;     __device__ __forceinline__ void operator()(const f32x4 (&acc)[2][2][4][2], const Unit& u, int wr, int wc, int fr, int fq) const {
;     ...
;             for (int m = 0; m < 4; ++m) rs[ai][m] = __builtin_amdgcn_rsqf((float)ss[u.pm * BM + ai * HALF + wr * 64 + m * 16 + fr] * (1.f / (2048.f * 262144.f)) + 1e-6f);
; #pragma unroll
;         for (int n = 0; n < 2; ++n) {
;             const int cbase = 128 * u.pn + 32 * wc + 16 * n + 4 * fq;
;             const f32x4 w0 = *(const f32x4*)(cw + cbase), w1 = *(const f32x4*)(cw + FF + cbase), w2 = *(const f32x4*)(cw + 2 * FF + cbase), b4 = *(const f32x4*)(cb + cbase);
; #pragma unroll
;             for (int ai = 0; ai < 2; ++ai) {
;                 const int slab = u.pm * 4 + 2 * ai + wr;
;                 f32x4 r1p = (f32x4){0.f, 0.f, 0.f, 0.f}, r2p = (f32x4){0.f, 0.f, 0.f, 0.f};
; #pragma unroll
;                 for (int m = 0; m < 4; ++m) {
;                     const f32x4 g = acc[ai][1][m][n] * rs[ai][m], v = acc[ai][0][m][n] * rs[ai][m];
;                     f32x4 r1, r2, a;
; #pragma unroll
;                     for (int e = 0; e < 4; ++e) { r1[e] = __shfl(g[e], src1); r2[e] = __shfl(g[e], src2); }
; #pragma unroll
;                     for (int e = 0; e < 4; ++e) {
;                         const float p1 = fr >= 1 ? r1[e] : r1p[e], p2 = fr >= 2 ? r2[e] : r2p[e];
;                         const float gg = b4[e] + w0[e] * p2 + w1[e] * p1 + w2[e] * g[e];
;                         a[e] = gg * __builtin_amdgcn_rcpf(1.f + __expf(-gg)) * v[e];
;                     }
;                     r1p = r1; r2p = r2;
;                     const size_t row = (size_t)(u.pm * BM + ai * HALF + wr * 64 + m * 16 + fr);
;                     if (m == 0 && fr < 2) {
;                         *(f32x4*)(GF + (size_t)(slab * 2 + fr) * FF + cbase) = g; *(f32x4*)(VF + (size_t)(slab * 2 + fr) * FF + cbase) = v;
;                     } else {
;                         typedef unsigned u32x2v __attribute__((ext_vector_type(2)));
;                         u32x2v w; w.x = cvt_pk_bf16(a[0], a[1]); w.y = cvt_pk_bf16(a[2], a[3]);
;                         *(u32x2v*)(ACT + row * FF + cbase) = w;
;                     }
;                     if (m == 3 && fr >= 14) *(f32x4*)(GL + (size_t)(slab * 2 + fr - 14) * FF + cbase) = g;
.LBB0_63:
	s_or_b64 exec, exec, s[10:11]
	s_nop 0
	v_mov_b32_e32 v26, v94
	v_mov_b32_e32 v27, v94
	v_pk_mul_f32 v[24:25], v[24:25], v[26:27]
	s_nop 1
	v_mov_b32_dpp v31, v25 row_ror:1 row_mask:0xf bank_mask:0xf
	v_mov_b32_dpp v35, v25 row_ror:2 row_mask:0xf bank_mask:0xf
	v_mov_b32_e32 v28, v25
	v_mov_b32_e32 v29, v81
	v_mov_b32_dpp v36, v24 row_ror:2 row_mask:0xf bank_mask:0xf
	s_waitcnt lgkmcnt(2)
	v_cndmask_b32_e64 v65, v31, v65, s[40:41]
	s_waitcnt lgkmcnt(1)
	v_cndmask_b32_e64 v25, v41, v35, s[42:43]
	v_fma_f32 v25, v69, v25, v73
	v_fma_f32 v25, v29, v65, v25
	v_fma_f32 v28, v28, v64, v25
	v_mul_f32_e32 v25, 0xbfb8aa3b, v28
	v_exp_f32_e32 v25, v25
	v_mov_b32_dpp v29, v24 row_ror:1 row_mask:0xf bank_mask:0xf
	v_pk_mul_f32 v[20:21], v[20:21], v[26:27]
	s_waitcnt lgkmcnt(1)
	v_cndmask_b32_e64 v27, v40, v36, s[42:43]
	v_add_f32_e32 v25, 1.0, v25
	v_rcp_f32_e32 v26, v25
	s_waitcnt lgkmcnt(0)
	v_cndmask_b32_e64 v77, v29, v77, s[40:41]
	v_fma_f32 v27, v68, v27, v72
	v_fma_f32 v25, v80, v77, v27
	v_mov_b32_e32 v95, v94
	v_fma_f32 v27, v24, v76, v25
	v_pk_mul_f32 v[22:23], v[22:23], v[94:95]
	v_mul_f32_e32 v24, 0xbfb8aa3b, v27
	s_nop 1
	v_mov_b32_dpp v33, v23 row_ror:1 row_mask:0xf bank_mask:0xf
	v_mov_b32_dpp v34, v23 row_ror:2 row_mask:0xf bank_mask:0xf
	v_exp_f32_e32 v24, v24
	v_mul_f32_e32 v25, v28, v26
	v_mov_b32_dpp v30, v22 row_ror:1 row_mask:0xf bank_mask:0xf
	v_mov_b32_dpp v32, v22 row_ror:2 row_mask:0xf bank_mask:0xf
	v_add_f32_e32 v24, 1.0, v24
	v_mul_f32_e32 v21, v21, v25
	v_rcp_f32_e32 v26, v24
	s_waitcnt lgkmcnt(3)
	v_cndmask_b32_e64 v63, v33, v63, s[40:41]
	v_mov_b32_e32 v24, v23
	s_waitcnt lgkmcnt(2)
	v_cndmask_b32_e64 v23, v39, v34, s[42:43]
	v_fma_f32 v23, v67, v23, v71
	v_fma_f32 v23, v79, v63, v23
	v_fma_f32 v24, v24, v62, v23
	v_mul_f32_e32 v23, 0xbfb8aa3b, v24
	v_exp_f32_e32 v25, v23
	s_waitcnt lgkmcnt(1)
	v_cndmask_b32_e64 v75, v30, v75, s[40:41]
	s_waitcnt lgkmcnt(0)
	v_cndmask_b32_e64 v28, v38, v32, s[42:43]
	v_fma_f32 v28, v66, v28, v70
	v_fma_f32 v23, v78, v75, v28
	v_fma_f32 v22, v22, v74, v23
	v_mul_f32_e32 v23, 0xbfb8aa3b, v22
	v_exp_f32_e32 v23, v23
	v_add_f32_e32 v25, 1.0, v25
	v_rcp_f32_e32 v25, v25
	v_pk_mul_f32 v[18:19], v[18:19], v[94:95]
	v_add_f32_e32 v23, 1.0, v23
	v_rcp_f32_e32 v23, v23
	v_mul_f32_e32 v24, v24, v25
	v_mul_f32_e32 v26, v27, v26
	v_mul_f32_e32 v19, v19, v24
	v_mul_f32_e32 v22, v22, v23
	v_mul_f32_e32 v18, v18, v22
	v_mul_f32_e32 v20, v20, v26
	v_cvt_pk_bf16_f32 v18, v18, v19
	v_cvt_pk_bf16_f32 v19, v20, v21
	s_nop 1
	v_permlane16_swap_b32_e32 v214, v18
	v_permlane16_swap_b32_e32 v215, v19
	v_mov_b32_e32 v220, v214
	v_mov_b32_e32 v221, v215
	v_mov_b32_e32 v222, v18
	v_mov_b32_e32 v223, v19
	v_add_co_u32_e64 v98, s[98:99], v98, v205
	s_nop 1
	v_addc_co_u32_e64 v99, s[98:99], 0, v99, s[98:99]
	global_store_dwordx4 v[98:99], v[220:223], off nt
	v_mov_b32_e32 v18, v92
	v_mov_b32_e32 v19, v92
	v_pk_mul_f32 v[16:17], v[16:17], v[18:19]
	s_nop 1
	v_mov_b32_dpp v23, v17 row_ror:1 row_mask:0xf bank_mask:0xf
	v_mov_b32_dpp v27, v17 row_ror:2 row_mask:0xf bank_mask:0xf
	v_mov_b32_e32 v20, v17
	v_mov_b32_e32 v21, v81
	v_mov_b32_dpp v28, v16 row_ror:2 row_mask:0xf bank_mask:0xf
	s_waitcnt lgkmcnt(2)
	v_cndmask_b32_e64 v65, v23, v31, s[40:41]
	s_waitcnt lgkmcnt(1)
	v_cndmask_b32_e64 v17, v35, v27, s[42:43]
	v_fma_f32 v17, v69, v17, v73
	v_fma_f32 v17, v21, v65, v17
	v_fma_f32 v20, v20, v64, v17
	v_mul_f32_e32 v17, 0xbfb8aa3b, v20
	v_exp_f32_e32 v17, v17
	v_mov_b32_dpp v21, v16 row_ror:1 row_mask:0xf bank_mask:0xf
	v_pk_mul_f32 v[12:13], v[12:13], v[18:19]
	s_waitcnt lgkmcnt(1)
	v_cndmask_b32_e64 v19, v36, v28, s[42:43]
	v_add_f32_e32 v17, 1.0, v17
	v_rcp_f32_e32 v18, v17
	s_waitcnt lgkmcnt(0)
	v_cndmask_b32_e64 v77, v21, v29, s[40:41]
	v_fma_f32 v19, v68, v19, v72
	v_fma_f32 v17, v80, v77, v19
	v_mov_b32_e32 v93, v92
	v_fma_f32 v19, v16, v76, v17
	v_pk_mul_f32 v[14:15], v[14:15], v[92:93]
	v_mul_f32_e32 v16, 0xbfb8aa3b, v19
	s_nop 1
	v_mov_b32_dpp v25, v15 row_ror:1 row_mask:0xf bank_mask:0xf
	v_mov_b32_dpp v26, v15 row_ror:2 row_mask:0xf bank_mask:0xf
	v_exp_f32_e32 v16, v16
	v_mul_f32_e32 v17, v20, v18
	v_mov_b32_dpp v22, v14 row_ror:1 row_mask:0xf bank_mask:0xf
	v_mov_b32_dpp v24, v14 row_ror:2 row_mask:0xf bank_mask:0xf
	v_add_f32_e32 v16, 1.0, v16
	v_mul_f32_e32 v13, v13, v17
	v_rcp_f32_e32 v18, v16
	s_waitcnt lgkmcnt(3)
;     __device__ __forceinline__ void operator()(const f32x4 (&acc)[2][2][4][2], const Unit& u, int wr, int wc, int fr, int fq) const {
;     ...
;             for (int m = 0; m < 4; ++m) rs[ai][m] = __builtin_amdgcn_rsqf((float)ss[u.pm * BM + ai * HALF + wr * 64 + m * 16 + fr] * (1.f / (2048.f * 262144.f)) + 1e-6f);
; #pragma unroll
;         for (int n = 0; n < 2; ++n) {
;             const int cbase = 128 * u.pn + 32 * wc + 16 * n + 4 * fq;
;             const f32x4 w0 = *(const f32x4*)(cw + cbase), w1 = *(const f32x4*)(cw + FF + cbase), w2 = *(const f32x4*)(cw + 2 * FF + cbase), b4 = *(const f32x4*)(cb + cbase);
; #pragma unroll
;             for (int ai = 0; ai < 2; ++ai) {
;                 const int slab = u.pm * 4 + 2 * ai + wr;
;                 f32x4 r1p = (f32x4){0.f, 0.f, 0.f, 0.f}, r2p = (f32x4){0.f, 0.f, 0.f, 0.f};
; #pragma unroll
;                 for (int m = 0; m < 4; ++m) {
;                     const f32x4 g = acc[ai][1][m][n] * rs[ai][m], v = acc[ai][0][m][n] * rs[ai][m];
;                     f32x4 r1, r2, a;
; #pragma unroll
;                     for (int e = 0; e < 4; ++e) { r1[e] = __shfl(g[e], src1); r2[e] = __shfl(g[e], src2); }
; #pragma unroll
;                     for (int e = 0; e < 4; ++e) {
;                         const float p1 = fr >= 1 ? r1[e] : r1p[e], p2 = fr >= 2 ? r2[e] : r2p[e];
;                         const float gg = b4[e] + w0[e] * p2 + w1[e] * p1 + w2[e] * g[e];
;                         a[e] = gg * __builtin_amdgcn_rcpf(1.f + __expf(-gg)) * v[e];
;                     }
;                     r1p = r1; r2p = r2;
;                     const size_t row = (size_t)(u.pm * BM + ai * HALF + wr * 64 + m * 16 + fr);
;                     if (m == 0 && fr < 2) {
;                         *(f32x4*)(GF + (size_t)(slab * 2 + fr) * FF + cbase) = g; *(f32x4*)(VF + (size_t)(slab * 2 + fr) * FF + cbase) = v;
;                     } else {
;                         typedef unsigned u32x2v __attribute__((ext_vector_type(2)));
;                         u32x2v w; w.x = cvt_pk_bf16(a[0], a[1]); w.y = cvt_pk_bf16(a[2], a[3]);
;                         *(u32x2v*)(ACT + row * FF + cbase) = w;
;                     }
;                     if (m == 3 && fr >= 14) *(f32x4*)(GL + (size_t)(slab * 2 + fr - 14) * FF + cbase) = g;
	v_cndmask_b32_e64 v63, v25, v33, s[40:41]
	v_mov_b32_e32 v16, v15
	s_waitcnt lgkmcnt(2)
	v_cndmask_b32_e64 v15, v34, v26, s[42:43]
	v_fma_f32 v15, v67, v15, v71
	v_fma_f32 v15, v79, v63, v15
	v_fma_f32 v16, v16, v62, v15
	v_mul_f32_e32 v15, 0xbfb8aa3b, v16
	v_exp_f32_e32 v17, v15
	s_waitcnt lgkmcnt(1)
	v_cndmask_b32_e64 v75, v22, v30, s[40:41]
	s_waitcnt lgkmcnt(0)
	v_cndmask_b32_e64 v20, v32, v24, s[42:43]
	v_fma_f32 v20, v66, v20, v70
	v_fma_f32 v15, v78, v75, v20
	v_fma_f32 v14, v14, v74, v15
	v_mul_f32_e32 v15, 0xbfb8aa3b, v14
	v_exp_f32_e32 v15, v15
	v_add_f32_e32 v17, 1.0, v17
	v_rcp_f32_e32 v17, v17
	v_pk_mul_f32 v[10:11], v[10:11], v[92:93]
	v_add_f32_e32 v15, 1.0, v15
	v_rcp_f32_e32 v15, v15
	v_mul_f32_e32 v16, v16, v17
	v_mul_f32_e32 v18, v19, v18
	v_mul_f32_e32 v11, v11, v16
	v_mul_f32_e32 v14, v14, v15
	v_mul_f32_e32 v10, v10, v14
	v_mul_f32_e32 v12, v12, v18
	v_cvt_pk_bf16_f32 v10, v10, v11
	v_cvt_pk_bf16_f32 v11, v12, v13
	s_nop 1
	v_permlane16_swap_b32_e32 v216, v10
	v_permlane16_swap_b32_e32 v217, v11
	v_mov_b32_e32 v220, v216
	v_mov_b32_e32 v221, v217
	v_mov_b32_e32 v222, v10
	v_mov_b32_e32 v223, v11
	v_add_co_u32_e64 v96, s[98:99], v96, v205
	s_nop 1
	v_addc_co_u32_e64 v97, s[98:99], 0, v97, s[98:99]
	global_store_dwordx4 v[96:97], v[220:223], off nt
	v_mov_b32_e32 v10, v90
	v_mov_b32_e32 v11, v90
	v_pk_mul_f32 v[8:9], v[8:9], v[10:11]
	s_nop 1
	v_mov_b32_dpp v12, v9 row_ror:1 row_mask:0xf bank_mask:0xf
	v_mov_b32_dpp v18, v9 row_ror:2 row_mask:0xf bank_mask:0xf
	v_mov_b32_dpp v19, v8 row_ror:2 row_mask:0xf bank_mask:0xf
	v_pk_mul_f32 v[4:5], v[4:5], v[10:11]
	s_waitcnt lgkmcnt(2)
	v_cndmask_b32_e64 v65, v12, v23, s[40:41]
	s_waitcnt lgkmcnt(1)
	v_cndmask_b32_e64 v18, v27, v18, s[42:43]
	v_fma_f32 v18, v69, v18, v73
	v_fma_f32 v13, v81, v65, v18
	v_fma_f32 v12, v9, v64, v13
	v_mul_f32_e32 v13, 0xbfb8aa3b, v12
	v_exp_f32_e32 v13, v13
	v_mov_b32_dpp v18, v8 row_ror:1 row_mask:0xf bank_mask:0xf
	v_mov_b32_e32 v91, v90
	v_add_f32_e32 v10, 1.0, v13
	v_rcp_f32_e32 v13, v10
	s_waitcnt lgkmcnt(0)
	v_cndmask_b32_e64 v77, v18, v21, s[40:41]
	v_cndmask_b32_e64 v18, v28, v19, s[42:43]
	v_fma_f32 v18, v68, v18, v72
	v_fma_f32 v11, v80, v77, v18
	v_fma_f32 v18, v8, v76, v11
	v_pk_mul_f32 v[6:7], v[6:7], v[90:91]
	v_mul_f32_e32 v10, 0xbfb8aa3b, v18
	s_nop 1
	v_mov_b32_dpp v16, v7 row_ror:1 row_mask:0xf bank_mask:0xf
	v_mov_b32_dpp v17, v7 row_ror:2 row_mask:0xf bank_mask:0xf
	v_exp_f32_e32 v10, v10
	v_mul_f32_e32 v11, v12, v13
	v_mov_b32_dpp v14, v6 row_ror:1 row_mask:0xf bank_mask:0xf
	v_mov_b32_dpp v15, v6 row_ror:2 row_mask:0xf bank_mask:0xf
	v_add_f32_e32 v10, 1.0, v10
	v_mul_f32_e32 v5, v5, v11
	v_rcp_f32_e32 v12, v10
	s_waitcnt lgkmcnt(3)
	v_cndmask_b32_e64 v63, v16, v25, s[40:41]
	s_waitcnt lgkmcnt(2)
	v_cndmask_b32_e64 v13, v26, v17, s[42:43]
	v_fma_f32 v13, v67, v13, v71
	v_fma_f32 v11, v79, v63, v13
	v_fma_f32 v13, v7, v62, v11
	v_mul_f32_e32 v10, 0xbfb8aa3b, v13
	v_exp_f32_e32 v16, v10
	s_waitcnt lgkmcnt(1)
	v_cndmask_b32_e64 v75, v14, v22, s[40:41]
	s_waitcnt lgkmcnt(0)
	v_cndmask_b32_e64 v14, v24, v15, s[42:43]
	v_fmac_f32_e32 v70, v66, v14
	v_fma_f32 v11, v78, v75, v70
	v_fma_f32 v10, v6, v74, v11
	v_mul_f32_e32 v11, 0xbfb8aa3b, v10
	v_exp_f32_e32 v11, v11
	v_add_f32_e32 v14, 1.0, v16
	v_rcp_f32_e32 v14, v14
	v_mul_f32_e32 v12, v18, v12
	v_add_f32_e32 v11, 1.0, v11
	v_rcp_f32_e32 v11, v11
	v_pk_mul_f32 v[2:3], v[2:3], v[90:91]
	v_mul_f32_e32 v4, v4, v12
	v_mul_f32_e32 v12, v13, v14
	v_mul_f32_e32 v10, v10, v11
	v_mul_f32_e32 v3, v3, v12
	v_mul_f32_e32 v2, v2, v10
	v_cvt_pk_bf16_f32 v2, v2, v3
	v_cvt_pk_bf16_f32 v3, v4, v5
	s_nop 1
	v_permlane16_swap_b32_e32 v218, v2
	v_permlane16_swap_b32_e32 v219, v3
	v_mov_b32_e32 v220, v218
	v_mov_b32_e32 v221, v219
	v_mov_b32_e32 v222, v2
	v_mov_b32_e32 v223, v3
	v_add_co_u32_e64 v88, s[98:99], v88, v205
	s_nop 1
	v_addc_co_u32_e64 v89, s[98:99], 0, v89, s[98:99]
	global_store_dwordx4 v[88:89], v[220:223], off nt
	s_and_saveexec_b64 s[10:11], s[44:45]
	s_cbranch_execz .LBB0_65
	global_store_dwordx4 v[86:87], v[6:9], off offset:64
